# FFT stage-1 tiles (both lengths) staged row-major with coalesced row reads and ds_read_b64_tr_b16 fragments
# speedup vs baseline: 1.0230x; 1.0025x over previous
; __device__ __forceinline__ int otid(int wv) { int t; asm volatile("v_mbcnt_lo_u32_b32 %0, -1, 0\n\tv_mbcnt_hi_u32_b32 %0, -1, %0\n\tv_lshl_add_u32 %0, %1, 6, %0" : "=&v"(t) : "s"(wv)); return t; }
; template <int N1> __device__ void fft1_units(int wv, const Params& p, unsigned char* lds, int seq_lo, int nseq, int part, int nparts) {
;     const int tid = otid(wv), lane = tid & 63, w = __builtin_amdgcn_readfirstlane(tid >> 6), lr = lane & 15, lq = lane >> 4;
;     constexpr int PW = N1 + 8, NB = N1 / 16, NK = N1 / 32; constexpr int S = N1 * 128;
;     const bf16_t* z = (const bf16_t*)(p.ws + WS_BIG1); bf16_t* A1 = (bf16_t*)(p.ws + WS_BIG2);
;     const bf16_t* ctg = (const bf16_t*)(p.ws + WS_TAB + (N1 == 64 ? TAB_CT64 : TAB_CT128)); const bf16_t* stg = (const bf16_t*)(p.ws + WS_TAB + (N1 == 64 ? TAB_ST64 : TAB_ST128));
;     bf16_t* CT = (bf16_t*)lds; bf16_t* ST = CT + N1 * PW; bf16_t* XT = ST + N1 * PW;
;     for (int idx = tid; idx < N1 * N1 / 8; idx += NTHR) { const int r = idx / (N1 / 8), c8 = (idx % (N1 / 8)) * 8;
;         *(bf16x8*)(CT + r * PW + c8) = *(const bf16x8*)(ctg + r * N1 + c8); *(bf16x8*)(ST + r * PW + c8) = *(const bf16x8*)(stg + r * N1 + c8); }
;     __syncthreads();
;     const int nunits = nseq * 128 * 8;
;     for (int unit = part; unit < nunits; unit += nparts) {
;         const int sq = unit / 1024, b = (unit >> 3) & 127, cb = unit & 7;
;         const int seq = seq_lo + sq; const size_t sbase = (size_t)seq * 8192;
;         for (int idx = tid; idx < N1 * 16; idx += NTHR) { const int a = idx % N1, c8 = (idx / N1) * 8;
;             const bf16x8 v = *(const bf16x8*)(z + (sbase + 128 * a + b) * DM + cb * 128 + c8);
; #pragma unroll
;             for (int e = 0; e < 8; ++e) XT[(c8 + e) * PW + a] = (bf16_t)v[e]; }
;         __syncthreads();
;         bf16x8 xf[NK];
; #pragma unroll
;         for (int kk = 0; kk < NK; ++kk) xf[kk] = *(const bf16x8*)(XT + (16 * w + lr) * PW + 32 * kk + 8 * lq);
; #pragma unroll
;         for (int i = 0; i < NB; ++i) { f32x4 ar = {0, 0, 0, 0}, as = {0, 0, 0, 0};
; #pragma unroll
;             for (int kk = 0; kk < NK; ++kk) { const bf16x8 cf = *(const bf16x8*)(CT + (16 * i + lr) * PW + 32 * kk + 8 * lq), sf = *(const bf16x8*)(ST + (16 * i + lr) * PW + 32 * kk + 8 * lq);
;                 ar = mfma16(xf[kk], cf, ar); as = mfma16(xf[kk], sf, as); }
.LBB0_313:
	s_or_b64 exec, exec, s[6:7]
	v_readlane_b32 s6, v254, 16
	v_readlane_b32 s7, v254, 17
	s_andn2_b64 vcc, exec, s[6:7]
	s_waitcnt lgkmcnt(0)
	s_barrier
	s_cbranch_vccnz .LBB0_319
	s_ashr_i32 s7, s14, 2
	s_and_b32 s6, s7, -16
	v_bfi_b32 v3, -16, s7, v1
	s_movk_i32 s7, 0x110
	v_mul_lo_u32 v3, v3, s7
	s_ashr_i32 s7, s6, 31
	s_lshl_b64 s[6:7], s[6:7], 1
	v_readlane_b32 s10, v254, 13
	v_bfe_u32 v2, v1, 4, 2
	v_readlane_b32 s14, v254, 57
	v_readlane_b32 s11, v254, 14
	s_add_u32 s6, s10, s6
	v_and_b32_e32 v4, 15, v1
	v_add_u32_e32 v5, s14, v3
	v_lshlrev_b32_e32 v6, 4, v2
	v_lshlrev_b32_e32 v2, 3, v2
	s_addc_u32 s7, s11, s7
	v_mov_b32_e32 v3, v0
	v_lshl_add_u64 v[18:19], s[6:7], 0, v[2:3]
	v_or_b32_e32 v3, 32, v4
	v_add_u32_e32 v7, 0, v6
	v_or_b32_e32 v8, 48, v4
	v_mul_u32_u24_e32 v9, 0x88, v3
	v_lshl_add_u32 v23, v9, 1, v7
	v_mul_u32_u24_e32 v9, 0x88, v8
	v_lshl_add_u32 v25, v9, 1, v7
	v_or_b32_e32 v9, 64, v4
	v_or_b32_e32 v10, 0x50, v4
	v_mul_u32_u24_e32 v11, 0x88, v9
	v_lshl_add_u32 v27, v11, 1, v7
	v_mul_u32_u24_e32 v11, 0x88, v10
	v_lshl_add_u32 v38, v11, 1, v7
	v_or_b32_e32 v11, 0x60, v4
	v_mul_u32_u24_e32 v2, 0x88, v4
	v_or_b32_e32 v12, 0x70, v4
	v_mul_u32_u24_e32 v13, 0x88, v11
	v_lshl_add_u32 v21, v2, 1, v7
	v_or_b32_e32 v2, 16, v4
	v_lshl_add_u32 v39, v13, 1, v7
	v_mul_u32_u24_e32 v13, 0x88, v12
	v_lshlrev_b32_e32 v20, 7, v4
	v_lshlrev_b32_e32 v22, 7, v2
	v_lshlrev_b32_e32 v24, 7, v3
	v_lshlrev_b32_e32 v26, 7, v8
	v_lshlrev_b32_e32 v28, 7, v9
	v_mov_b32_e32 v29, v0
	v_lshlrev_b32_e32 v30, 7, v10
	v_mov_b32_e32 v31, v0
	v_lshlrev_b32_e32 v32, 7, v11
	v_mov_b32_e32 v33, v0
	v_lshl_add_u32 v40, v13, 1, v7
	v_lshlrev_b32_e32 v34, 7, v12
	v_mov_b32_e32 v35, v0
	v_lshlrev_b32_e32 v41, 1, v2
	v_lshlrev_b32_e32 v42, 1, v4
	v_lshlrev_b32_e32 v43, 1, v8
	v_lshlrev_b32_e32 v44, 1, v3
	v_lshlrev_b32_e32 v45, 1, v10
	v_lshlrev_b32_e32 v46, 1, v9
	v_lshlrev_b32_e32 v47, 1, v12
	v_lshlrev_b32_e32 v48, 1, v11
	v_lshlrev_b32_e32 v49, 7, v1
	v_lshl_add_u32 v50, v1, 1, s14
	v_add_u32_e32 v51, v5, v6
	v_readlane_b32 s20, v254, 15
	v_mbcnt_lo_u32_b32 v224, -1, 0
	v_mbcnt_hi_u32_b32 v224, -1, v224
	v_lshl_add_u32 v225, s33, 6, v224
	v_lshrrev_b32_e32 v226, 4, v225
	v_and_b32_e32 v227, 15, v225
	v_and_b32_e32 v228, 3, v226
	v_lshlrev_b32_e32 v228, 2, v228
	v_bfe_u32 v229, v226, 2, 2
	v_or_b32_e32 v228, v228, v229
	v_xor_b32_e32 v228, v227, v228
	v_lshlrev_b32_e32 v228, 4, v228
	v_lshl_add_u32 v202, v226, 8, v228
	v_add_u32_e32 v202, 0x11000, v202
	v_lshlrev_b32_e32 v200, 18, v226
	v_lshl_add_u32 v200, v227, 4, v200
	v_mov_b32_e32 v201, 0
	v_bfe_u32 v226, v224, 2, 2
	v_and_b32_e32 v227, 3, v224
	v_lshrrev_b32_e32 v228, 4, v224
	v_lshl_add_u32 v229, v228, 3, v226
	v_lshlrev_b32_e32 v230, 2, v226
	v_lshlrev_b32_e32 v228, 1, v228
	v_and_b32_e32 v231, 3, v228
	v_or_b32_e32 v231, v230, v231
	v_add_u32_e32 v228, 1, v228
	v_and_b32_e32 v228, 3, v228
	v_or_b32_e32 v228, v230, v228
	s_lshl_b32 s14, s33, 1
	v_lshrrev_b32_e32 v230, 1, v227
	v_add_u32_e32 v230, s14, v230
	v_and_b32_e32 v227, 1, v227
	v_lshlrev_b32_e32 v227, 3, v227
	v_xor_b32_e32 v231, v230, v231
	v_lshl_add_u32 v231, v231, 4, v227
	v_lshl_add_u32 v222, v229, 8, v231
	v_add_u32_e32 v222, 0x11000, v222
	v_xor_b32_e32 v228, v230, v228
	v_lshl_add_u32 v228, v228, 4, v227
	v_add_u32_e32 v229, 4, v229
	v_lshl_add_u32 v223, v229, 8, v228
	v_add_u32_e32 v223, 0x11000, v223
	s_branch .LBB0_316
.LBB0_315:
	s_or_b64 exec, exec, s[10:11]
	s_waitcnt lgkmcnt(0)
	s_barrier
	ds_read_b64_tr_b16 v[14:15], v222
	ds_read_b64_tr_b16 v[16:17], v223
	ds_read_b64_tr_b16 v[10:11], v222 offset:8192
	ds_read_b64_tr_b16 v[12:13], v223 offset:8192
	ds_read_b64_tr_b16 v[6:7], v222 offset:16384
	ds_read_b64_tr_b16 v[8:9], v223 offset:16384
	ds_read_b64_tr_b16 v[2:3], v222 offset:24576
	ds_read_b64_tr_b16 v[4:5], v223 offset:24576
	ds_read_b128 v[52:55], v21
	ds_read_b128 v[56:59], v21 offset:34816
	ds_read_b128 v[60:63], v21 offset:64
	ds_read_b128 v[64:67], v21 offset:34880
	s_waitcnt lgkmcnt(3)
	v_mfma_f32_16x16x32_bf16 v[52:55], v[14:17], v[52:55], 0
	s_lshl_b32 s36, s22, 1
	v_lshl_add_u64 v[36:37], v[18:19], 0, s[36:37]
	v_mul_u32_u24_e32 v78, s21, v41
	s_waitcnt lgkmcnt(2)
	v_mfma_f32_16x16x32_bf16 v[56:59], v[14:17], v[56:59], 0
	v_mul_u32_u24_e32 v79, s21, v42
	s_mov_b32 s14, 0x38800000
	s_mov_b32 s10, 0x7f800000
	s_waitcnt lgkmcnt(1)
	v_mfma_f32_16x16x32_bf16 v[52:55], v[10:13], v[60:63], v[52:55]
	v_mov_b32_e32 v82, 0xbf1f24be
	v_mov_b32_e32 v83, 0x3e642e9d
	s_brev_b32 s11, 1
	s_waitcnt lgkmcnt(0)
	v_mfma_f32_16x16x32_bf16 v[56:59], v[10:13], v[64:67], v[56:59]
	ds_read_b128 v[60:63], v21 offset:128
	ds_read_b128 v[64:67], v21 offset:34944
	v_mov_b32_e32 v84, 0x7fc00000
	s_add_i32 s20, s20, s40
	s_waitcnt lgkmcnt(1)
	v_mfma_f32_16x16x32_bf16 v[52:55], v[6:9], v[60:63], v[52:55]
	s_cmpk_gt_i32 s20, 0x3ff
	s_waitcnt lgkmcnt(0)
	v_mfma_f32_16x16x32_bf16 v[56:59], v[6:9], v[64:67], v[56:59]
	ds_read_b128 v[60:63], v21 offset:192
	ds_read_b128 v[64:67], v21 offset:35008
	s_waitcnt lgkmcnt(1)
	v_mfma_f32_16x16x32_bf16 v[52:55], v[2:5], v[60:63], v[52:55]
	v_mov_b32_e32 v61, s7
	v_or_b32_e32 v60, s6, v20
	v_lshlrev_b64 v[60:61], 12, v[60:61]
	s_waitcnt lgkmcnt(0)
	v_mfma_f32_16x16x32_bf16 v[56:59], v[2:5], v[64:67], v[56:59]
	v_lshl_add_u64 v[76:77], v[36:37], 0, v[60:61]
	ds_read_b128 v[60:63], v21 offset:4352
	ds_read_b128 v[64:67], v21 offset:39168
	ds_read_b128 v[68:71], v21 offset:4416
	ds_read_b128 v[72:75], v21 offset:39232
	s_waitcnt lgkmcnt(3)
	v_mfma_f32_16x16x32_bf16 v[60:63], v[14:17], v[60:63], 0
	s_waitcnt lgkmcnt(2)
	v_mfma_f32_16x16x32_bf16 v[64:67], v[14:17], v[64:67], 0
	s_waitcnt lgkmcnt(1)
; __device__ __forceinline__ unsigned cvt_pk_bf16(float lo, float hi) { const f2_t v = {lo, hi}; const bf2_t b = __builtin_convertvector(v, bf2_t); return __builtin_bit_cast(unsigned, b); }
; __device__ __forceinline__ f32x4 mfma16(bf16x8 a, bf16x8 b, f32x4 c) { return __builtin_amdgcn_mfma_f32_16x16x32_bf16(a, b, c, 0, 0, 0); }
; template <int N1> __device__ void fft1_units(int wv, const Params& p, unsigned char* lds, int seq_lo, int nseq, int part, int nparts) {
;     ...
;         for (int i = 0; i < NB; ++i) { f32x4 ar = {0, 0, 0, 0}, as = {0, 0, 0, 0};
; #pragma unroll
;             for (int kk = 0; kk < NK; ++kk) { const bf16x8 cf = *(const bf16x8*)(CT + (16 * i + lr) * PW + 32 * kk + 8 * lq), sf = *(const bf16x8*)(ST + (16 * i + lr) * PW + 32 * kk + 8 * lq);
;                 ar = mfma16(xf[kk], cf, ar); as = mfma16(xf[kk], sf, as); }
;             const int ka = 16 * i + lr; float tc, ts; sincospif(2.0f * (float)(b * ka) / (float)S, &ts, &tc);
;             const f32x4 re = ar * tc - as * ts, im = -(as * tc) - ar * ts;
;             bf16_t* op = A1 + (sbase + (size_t)ka * 128 + b) * 2048 + cb * 128 + 16 * w + 4 * lq;
;             u32x2 o; o.x = cvt_pk_bf16(re[0], re[1]); o.y = cvt_pk_bf16(re[2], re[3]); *(u32x2*)op = o;
;             o.x = cvt_pk_bf16(im[0], im[1]); o.y = cvt_pk_bf16(im[2], im[3]); *(u32x2*)(op + 1024) = o; }
	v_mfma_f32_16x16x32_bf16 v[60:63], v[10:13], v[68:71], v[60:63]
	s_waitcnt lgkmcnt(0)
	v_mfma_f32_16x16x32_bf16 v[64:67], v[10:13], v[72:75], v[64:67]
	ds_read_b128 v[68:71], v21 offset:4480
	ds_read_b128 v[72:75], v21 offset:39296
	s_waitcnt lgkmcnt(1)
	v_mfma_f32_16x16x32_bf16 v[60:63], v[6:9], v[68:71], v[60:63]
	s_waitcnt lgkmcnt(0)
	v_mfma_f32_16x16x32_bf16 v[64:67], v[6:9], v[72:75], v[64:67]
	ds_read_b128 v[68:71], v21 offset:4544
	ds_read_b128 v[72:75], v21 offset:39360
	s_waitcnt lgkmcnt(1)
	v_mfma_f32_16x16x32_bf16 v[60:63], v[2:5], v[68:71], v[60:63]
	v_cvt_f32_u32_e32 v69, v79
	v_cvt_f32_u32_e32 v68, v78
	v_pk_mul_f32 v[68:69], v[68:69], s[14:15] op_sel_hi:[1,0]
	s_nop 0
	v_pk_mul_f32 v[70:71], v[68:69], 0.5 op_sel_hi:[1,0]
	s_waitcnt lgkmcnt(0)
	v_mfma_f32_16x16x32_bf16 v[64:67], v[2:5], v[72:75], v[64:67]
	v_fract_f32_e32 v72, v71
	v_add_f32_e32 v72, v72, v72
	v_cmp_neq_f32_e32 vcc, s10, v71
	s_nop 1
	v_cndmask_b32_e32 v71, 0, v72, vcc
	v_cmp_lt_f32_e32 vcc, 1.0, v69
	s_nop 1
	v_cndmask_b32_e32 v71, v69, v71, vcc
	v_add_f32_e32 v72, v71, v71
	v_rndne_f32_e32 v72, v72
	v_fmac_f32_e32 v71, -0.5, v72
	v_mul_f32_e32 v73, v71, v71
	v_fmamk_f32 v74, v73, 0x3e75aa41, v82
	v_fmaak_f32 v74, v73, v74, 0x40234736
	v_fmaak_f32 v74, v73, v74, 0xc0a55e0e
	v_mul_f32_e32 v75, v71, v73
	v_mul_f32_e32 v74, v75, v74
	v_cvt_i32_f32_e32 v72, v72
	v_fmac_f32_e32 v74, 0x40490fdb, v71
	v_fmamk_f32 v71, v73, 0x3d4be544, v83
	v_fmaak_f32 v71, v73, v71, 0xbfaad1da
	v_fmaak_f32 v71, v73, v71, 0x4081e0d3
	v_fmaak_f32 v71, v73, v71, 0xc09de9e6
	v_fma_f32 v71, v73, v71, 1.0
	v_lshlrev_b32_e32 v73, 30, v72
	v_and_b32_e32 v72, 1, v72
	v_cmp_eq_u32_e32 vcc, 0, v72
	s_nop 1
	v_cndmask_b32_e32 v72, v71, v74, vcc
	v_bitop3_b32 v75, v72, v73, s11 bitop3:0x78
	v_xor_b32_e32 v72, 0x80000000, v74
	v_cndmask_b32_e32 v71, v72, v71, vcc
	v_cmp_lg_f32_e32 vcc, s10, v69
	v_bitop3_b32 v71, v71, v73, s11 bitop3:0x78
	s_nop 0
	v_cndmask_b32_e32 v74, v84, v75, vcc
	v_cndmask_b32_e32 v72, v84, v71, vcc
	v_pk_mul_f32 v[78:79], v[74:75], v[56:57] op_sel_hi:[0,1]
	v_pk_mul_f32 v[80:81], v[74:75], v[58:59] op_sel_hi:[0,1]
	v_pk_fma_f32 v[80:81], v[72:73], v[54:55], v[80:81] op_sel_hi:[0,1,1] neg_lo:[0,0,1] neg_hi:[0,0,1]
	v_pk_fma_f32 v[78:79], v[72:73], v[52:53], v[78:79] op_sel_hi:[0,1,1] neg_lo:[0,0,1] neg_hi:[0,0,1]
	v_pk_mul_f32 v[52:53], v[74:75], v[52:53] op_sel_hi:[0,1]
	v_pk_mul_f32 v[54:55], v[74:75], v[54:55] op_sel_hi:[0,1]
	v_pk_fma_f32 v[54:55], v[58:59], v[72:73], v[54:55] op_sel_hi:[1,0,1] neg_lo:[0,1,1] neg_hi:[0,1,1]
	v_pk_fma_f32 v[52:53], v[56:57], v[72:73], v[52:53] op_sel_hi:[1,0,1] neg_lo:[0,1,1] neg_hi:[0,1,1]
	v_cmp_neq_f32_e32 vcc, s10, v70
	v_cvt_pk_bf16_f32 v52, v52, v53
	v_cvt_pk_bf16_f32 v53, v54, v55
	global_store_dwordx2 v[76:77], v[52:53], off offset:2048
	v_fract_f32_e32 v52, v70
	v_add_f32_e32 v52, v52, v52
	v_cndmask_b32_e32 v52, 0, v52, vcc
	v_cmp_lt_f32_e32 vcc, 1.0, v68
	v_cvt_pk_bf16_f32 v56, v78, v79
	v_cvt_pk_bf16_f32 v57, v80, v81
	v_cndmask_b32_e32 v52, v68, v52, vcc
	v_add_f32_e32 v53, v52, v52
	v_rndne_f32_e32 v53, v53
	v_fmac_f32_e32 v52, -0.5, v53
	v_mul_f32_e32 v54, v52, v52
	v_fmamk_f32 v55, v54, 0x3e75aa41, v82
	v_fmaak_f32 v55, v54, v55, 0x40234736
	global_store_dwordx2 v[76:77], v[56:57], off
	v_fmaak_f32 v55, v54, v55, 0xc0a55e0e
	v_mul_f32_e32 v56, v52, v54
	v_mul_f32_e32 v55, v56, v55
	v_cvt_i32_f32_e32 v53, v53
	v_fmac_f32_e32 v55, 0x40490fdb, v52
	v_fmamk_f32 v52, v54, 0x3d4be544, v83
	v_fmaak_f32 v52, v54, v52, 0xbfaad1da
	v_fmaak_f32 v52, v54, v52, 0x4081e0d3
	v_fmaak_f32 v52, v54, v52, 0xc09de9e6
	v_fma_f32 v52, v54, v52, 1.0
	v_lshlrev_b32_e32 v54, 30, v53
	v_and_b32_e32 v53, 1, v53
	v_cmp_eq_u32_e32 vcc, 0, v53
	v_mul_u32_u24_e32 v78, s21, v43
	v_mul_u32_u24_e32 v79, s21, v44
	v_cndmask_b32_e32 v53, v52, v55, vcc
	v_xor_b32_e32 v55, 0x80000000, v55
	v_bitop3_b32 v53, v53, v54, s11 bitop3:0x78
	v_cndmask_b32_e32 v52, v55, v52, vcc
	v_cmp_lg_f32_e32 vcc, s10, v68
	v_bitop3_b32 v52, v52, v54, s11 bitop3:0x78
	s_nop 0
	v_cndmask_b32_e32 v54, v84, v53, vcc
	v_cndmask_b32_e32 v52, v84, v52, vcc
	v_pk_mul_f32 v[56:57], v[54:55], v[64:65] op_sel_hi:[0,1]
	v_pk_mul_f32 v[58:59], v[54:55], v[66:67] op_sel_hi:[0,1]
	v_pk_fma_f32 v[56:57], v[52:53], v[60:61], v[56:57] op_sel_hi:[0,1,1] neg_lo:[0,0,1] neg_hi:[0,0,1]
	v_pk_mul_f32 v[60:61], v[54:55], v[60:61] op_sel_hi:[0,1]
	v_pk_mul_f32 v[54:55], v[54:55], v[62:63] op_sel_hi:[0,1]
	v_pk_fma_f32 v[58:59], v[52:53], v[62:63], v[58:59] op_sel_hi:[0,1,1] neg_lo:[0,0,1] neg_hi:[0,0,1]
	v_pk_fma_f32 v[54:55], v[66:67], v[52:53], v[54:55] op_sel_hi:[1,0,1] neg_lo:[0,1,1] neg_hi:[0,1,1]
	v_pk_fma_f32 v[52:53], v[64:65], v[52:53], v[60:61] op_sel_hi:[1,0,1] neg_lo:[0,1,1] neg_hi:[0,1,1]
	v_mov_b32_e32 v61, s7
	v_or_b32_e32 v60, s6, v22
	v_lshlrev_b64 v[60:61], 12, v[60:61]
	v_lshl_add_u64 v[60:61], v[36:37], 0, v[60:61]
	v_cvt_pk_bf16_f32 v56, v56, v57
	v_cvt_pk_bf16_f32 v57, v58, v59
	v_cvt_pk_bf16_f32 v52, v52, v53
	v_cvt_pk_bf16_f32 v53, v54, v55
	global_store_dwordx2 v[60:61], v[56:57], off
	global_store_dwordx2 v[60:61], v[52:53], off offset:2048
	ds_read_b128 v[52:55], v23
	ds_read_b128 v[56:59], v23 offset:34816
	ds_read_b128 v[60:63], v23 offset:64
	ds_read_b128 v[64:67], v23 offset:34880
	s_waitcnt lgkmcnt(3)
	v_mfma_f32_16x16x32_bf16 v[52:55], v[14:17], v[52:55], 0
	s_waitcnt lgkmcnt(2)
	v_mfma_f32_16x16x32_bf16 v[56:59], v[14:17], v[56:59], 0
	s_waitcnt lgkmcnt(1)
	v_mfma_f32_16x16x32_bf16 v[52:55], v[10:13], v[60:63], v[52:55]
	s_waitcnt lgkmcnt(0)
	v_mfma_f32_16x16x32_bf16 v[56:59], v[10:13], v[64:67], v[56:59]
	ds_read_b128 v[60:63], v23 offset:128
	ds_read_b128 v[64:67], v23 offset:34944
	s_waitcnt lgkmcnt(1)
; __device__ __forceinline__ unsigned cvt_pk_bf16(float lo, float hi) { const f2_t v = {lo, hi}; const bf2_t b = __builtin_convertvector(v, bf2_t); return __builtin_bit_cast(unsigned, b); }
; __device__ __forceinline__ f32x4 mfma16(bf16x8 a, bf16x8 b, f32x4 c) { return __builtin_amdgcn_mfma_f32_16x16x32_bf16(a, b, c, 0, 0, 0); }
; template <int N1> __device__ void fft1_units(int wv, const Params& p, unsigned char* lds, int seq_lo, int nseq, int part, int nparts) {
;     ...
;         for (int i = 0; i < NB; ++i) { f32x4 ar = {0, 0, 0, 0}, as = {0, 0, 0, 0};
; #pragma unroll
;             for (int kk = 0; kk < NK; ++kk) { const bf16x8 cf = *(const bf16x8*)(CT + (16 * i + lr) * PW + 32 * kk + 8 * lq), sf = *(const bf16x8*)(ST + (16 * i + lr) * PW + 32 * kk + 8 * lq);
;                 ar = mfma16(xf[kk], cf, ar); as = mfma16(xf[kk], sf, as); }
;             const int ka = 16 * i + lr; float tc, ts; sincospif(2.0f * (float)(b * ka) / (float)S, &ts, &tc);
;             const f32x4 re = ar * tc - as * ts, im = -(as * tc) - ar * ts;
;             bf16_t* op = A1 + (sbase + (size_t)ka * 128 + b) * 2048 + cb * 128 + 16 * w + 4 * lq;
;             u32x2 o; o.x = cvt_pk_bf16(re[0], re[1]); o.y = cvt_pk_bf16(re[2], re[3]); *(u32x2*)op = o;
;             o.x = cvt_pk_bf16(im[0], im[1]); o.y = cvt_pk_bf16(im[2], im[3]); *(u32x2*)(op + 1024) = o; }
	v_mfma_f32_16x16x32_bf16 v[52:55], v[6:9], v[60:63], v[52:55]
	s_waitcnt lgkmcnt(0)
	v_mfma_f32_16x16x32_bf16 v[56:59], v[6:9], v[64:67], v[56:59]
	ds_read_b128 v[60:63], v23 offset:192
	ds_read_b128 v[64:67], v23 offset:35008
	s_waitcnt lgkmcnt(1)
	v_mfma_f32_16x16x32_bf16 v[52:55], v[2:5], v[60:63], v[52:55]
	v_mov_b32_e32 v61, s7
	v_or_b32_e32 v60, s6, v24
	v_lshlrev_b64 v[60:61], 12, v[60:61]
	s_waitcnt lgkmcnt(0)
	v_mfma_f32_16x16x32_bf16 v[56:59], v[2:5], v[64:67], v[56:59]
	v_lshl_add_u64 v[76:77], v[36:37], 0, v[60:61]
	ds_read_b128 v[60:63], v25
	ds_read_b128 v[64:67], v25 offset:34816
	ds_read_b128 v[68:71], v25 offset:64
	ds_read_b128 v[72:75], v25 offset:34880
	s_waitcnt lgkmcnt(3)
	v_mfma_f32_16x16x32_bf16 v[60:63], v[14:17], v[60:63], 0
	s_waitcnt lgkmcnt(2)
	v_mfma_f32_16x16x32_bf16 v[64:67], v[14:17], v[64:67], 0
	s_waitcnt lgkmcnt(1)
	v_mfma_f32_16x16x32_bf16 v[60:63], v[10:13], v[68:71], v[60:63]
	s_waitcnt lgkmcnt(0)
	v_mfma_f32_16x16x32_bf16 v[64:67], v[10:13], v[72:75], v[64:67]
	ds_read_b128 v[68:71], v25 offset:128
	ds_read_b128 v[72:75], v25 offset:34944
	s_waitcnt lgkmcnt(1)
	v_mfma_f32_16x16x32_bf16 v[60:63], v[6:9], v[68:71], v[60:63]
	s_waitcnt lgkmcnt(0)
	v_mfma_f32_16x16x32_bf16 v[64:67], v[6:9], v[72:75], v[64:67]
	ds_read_b128 v[68:71], v25 offset:192
	ds_read_b128 v[72:75], v25 offset:35008
	s_waitcnt lgkmcnt(1)
	v_mfma_f32_16x16x32_bf16 v[60:63], v[2:5], v[68:71], v[60:63]
	v_cvt_f32_u32_e32 v69, v79
	v_cvt_f32_u32_e32 v68, v78
	v_pk_mul_f32 v[68:69], v[68:69], s[14:15] op_sel_hi:[1,0]
	s_nop 0
	v_pk_mul_f32 v[70:71], v[68:69], 0.5 op_sel_hi:[1,0]
	s_waitcnt lgkmcnt(0)
	v_mfma_f32_16x16x32_bf16 v[64:67], v[2:5], v[72:75], v[64:67]
	v_fract_f32_e32 v72, v71
	v_add_f32_e32 v72, v72, v72
	v_cmp_neq_f32_e32 vcc, s10, v71
	s_nop 1
	v_cndmask_b32_e32 v71, 0, v72, vcc
	v_cmp_lt_f32_e32 vcc, 1.0, v69
	s_nop 1
	v_cndmask_b32_e32 v71, v69, v71, vcc
	v_add_f32_e32 v72, v71, v71
	v_rndne_f32_e32 v72, v72
	v_fmac_f32_e32 v71, -0.5, v72
	v_mul_f32_e32 v73, v71, v71
	v_fmamk_f32 v74, v73, 0x3e75aa41, v82
	v_fmaak_f32 v74, v73, v74, 0x40234736
	v_fmaak_f32 v74, v73, v74, 0xc0a55e0e
	v_mul_f32_e32 v75, v71, v73
	v_mul_f32_e32 v74, v75, v74
	v_cvt_i32_f32_e32 v72, v72
	v_fmac_f32_e32 v74, 0x40490fdb, v71
	v_fmamk_f32 v71, v73, 0x3d4be544, v83
	v_fmaak_f32 v71, v73, v71, 0xbfaad1da
	v_fmaak_f32 v71, v73, v71, 0x4081e0d3
	v_fmaak_f32 v71, v73, v71, 0xc09de9e6
	v_fma_f32 v71, v73, v71, 1.0
	v_lshlrev_b32_e32 v73, 30, v72
	v_and_b32_e32 v72, 1, v72
	v_cmp_eq_u32_e32 vcc, 0, v72
	s_nop 1
	v_cndmask_b32_e32 v72, v71, v74, vcc
	v_bitop3_b32 v75, v72, v73, s11 bitop3:0x78
	v_xor_b32_e32 v72, 0x80000000, v74
	v_cndmask_b32_e32 v71, v72, v71, vcc
	v_cmp_lg_f32_e32 vcc, s10, v69
	v_bitop3_b32 v71, v71, v73, s11 bitop3:0x78
	s_nop 0
	v_cndmask_b32_e32 v74, v84, v75, vcc
	v_cndmask_b32_e32 v72, v84, v71, vcc
	v_pk_mul_f32 v[78:79], v[74:75], v[56:57] op_sel_hi:[0,1]
	v_pk_mul_f32 v[80:81], v[74:75], v[58:59] op_sel_hi:[0,1]
	v_pk_fma_f32 v[80:81], v[72:73], v[54:55], v[80:81] op_sel_hi:[0,1,1] neg_lo:[0,0,1] neg_hi:[0,0,1]
	v_pk_fma_f32 v[78:79], v[72:73], v[52:53], v[78:79] op_sel_hi:[0,1,1] neg_lo:[0,0,1] neg_hi:[0,0,1]
	v_pk_mul_f32 v[52:53], v[74:75], v[52:53] op_sel_hi:[0,1]
	v_pk_mul_f32 v[54:55], v[74:75], v[54:55] op_sel_hi:[0,1]
	v_pk_fma_f32 v[54:55], v[58:59], v[72:73], v[54:55] op_sel_hi:[1,0,1] neg_lo:[0,1,1] neg_hi:[0,1,1]
	v_pk_fma_f32 v[52:53], v[56:57], v[72:73], v[52:53] op_sel_hi:[1,0,1] neg_lo:[0,1,1] neg_hi:[0,1,1]
	v_cmp_neq_f32_e32 vcc, s10, v70
	v_cvt_pk_bf16_f32 v52, v52, v53
	v_cvt_pk_bf16_f32 v53, v54, v55
	global_store_dwordx2 v[76:77], v[52:53], off offset:2048
	v_fract_f32_e32 v52, v70
	v_add_f32_e32 v52, v52, v52
	v_cndmask_b32_e32 v52, 0, v52, vcc
	v_cmp_lt_f32_e32 vcc, 1.0, v68
	v_cvt_pk_bf16_f32 v56, v78, v79
	v_cvt_pk_bf16_f32 v57, v80, v81
	v_cndmask_b32_e32 v52, v68, v52, vcc
	v_add_f32_e32 v53, v52, v52
	v_rndne_f32_e32 v53, v53
	v_fmac_f32_e32 v52, -0.5, v53
	v_mul_f32_e32 v54, v52, v52
	v_fmamk_f32 v55, v54, 0x3e75aa41, v82
	v_fmaak_f32 v55, v54, v55, 0x40234736
	global_store_dwordx2 v[76:77], v[56:57], off
	v_fmaak_f32 v55, v54, v55, 0xc0a55e0e
	v_mul_f32_e32 v56, v52, v54
	v_mul_f32_e32 v55, v56, v55
	v_cvt_i32_f32_e32 v53, v53
	v_fmac_f32_e32 v55, 0x40490fdb, v52
	v_fmamk_f32 v52, v54, 0x3d4be544, v83
	v_fmaak_f32 v52, v54, v52, 0xbfaad1da
	v_fmaak_f32 v52, v54, v52, 0x4081e0d3
	v_fmaak_f32 v52, v54, v52, 0xc09de9e6
	v_fma_f32 v52, v54, v52, 1.0
	v_lshlrev_b32_e32 v54, 30, v53
	v_and_b32_e32 v53, 1, v53
	v_cmp_eq_u32_e32 vcc, 0, v53
	v_mul_u32_u24_e32 v78, s21, v45
	v_mul_u32_u24_e32 v79, s21, v46
	v_cndmask_b32_e32 v53, v52, v55, vcc
	v_xor_b32_e32 v55, 0x80000000, v55
	v_bitop3_b32 v53, v53, v54, s11 bitop3:0x78
	v_cndmask_b32_e32 v52, v55, v52, vcc
	v_cmp_lg_f32_e32 vcc, s10, v68
	v_bitop3_b32 v52, v52, v54, s11 bitop3:0x78
	s_nop 0
	v_cndmask_b32_e32 v54, v84, v53, vcc
	v_cndmask_b32_e32 v52, v84, v52, vcc
	v_pk_mul_f32 v[56:57], v[54:55], v[64:65] op_sel_hi:[0,1]
	v_pk_mul_f32 v[58:59], v[54:55], v[66:67] op_sel_hi:[0,1]
	v_pk_fma_f32 v[56:57], v[52:53], v[60:61], v[56:57] op_sel_hi:[0,1,1] neg_lo:[0,0,1] neg_hi:[0,0,1]
	v_pk_mul_f32 v[60:61], v[54:55], v[60:61] op_sel_hi:[0,1]
	v_pk_mul_f32 v[54:55], v[54:55], v[62:63] op_sel_hi:[0,1]
	v_pk_fma_f32 v[58:59], v[52:53], v[62:63], v[58:59] op_sel_hi:[0,1,1] neg_lo:[0,0,1] neg_hi:[0,0,1]
	v_pk_fma_f32 v[54:55], v[66:67], v[52:53], v[54:55] op_sel_hi:[1,0,1] neg_lo:[0,1,1] neg_hi:[0,1,1]
	v_pk_fma_f32 v[52:53], v[64:65], v[52:53], v[60:61] op_sel_hi:[1,0,1] neg_lo:[0,1,1] neg_hi:[0,1,1]
	v_mov_b32_e32 v61, s7
	v_or_b32_e32 v60, s6, v26
	v_lshlrev_b64 v[60:61], 12, v[60:61]
	v_lshl_add_u64 v[60:61], v[36:37], 0, v[60:61]
	v_cvt_pk_bf16_f32 v56, v56, v57
	v_cvt_pk_bf16_f32 v57, v58, v59
	v_cvt_pk_bf16_f32 v52, v52, v53
	v_cvt_pk_bf16_f32 v53, v54, v55
	global_store_dwordx2 v[60:61], v[56:57], off
	global_store_dwordx2 v[60:61], v[52:53], off offset:2048
	ds_read_b128 v[52:55], v27
	ds_read_b128 v[56:59], v27 offset:34816
	ds_read_b128 v[60:63], v27 offset:64
	ds_read_b128 v[64:67], v27 offset:34880
	s_waitcnt lgkmcnt(3)
; __device__ __forceinline__ unsigned cvt_pk_bf16(float lo, float hi) { const f2_t v = {lo, hi}; const bf2_t b = __builtin_convertvector(v, bf2_t); return __builtin_bit_cast(unsigned, b); }
; __device__ __forceinline__ f32x4 mfma16(bf16x8 a, bf16x8 b, f32x4 c) { return __builtin_amdgcn_mfma_f32_16x16x32_bf16(a, b, c, 0, 0, 0); }
; template <int N1> __device__ void fft1_units(int wv, const Params& p, unsigned char* lds, int seq_lo, int nseq, int part, int nparts) {
;     ...
;         for (int i = 0; i < NB; ++i) { f32x4 ar = {0, 0, 0, 0}, as = {0, 0, 0, 0};
; #pragma unroll
;             for (int kk = 0; kk < NK; ++kk) { const bf16x8 cf = *(const bf16x8*)(CT + (16 * i + lr) * PW + 32 * kk + 8 * lq), sf = *(const bf16x8*)(ST + (16 * i + lr) * PW + 32 * kk + 8 * lq);
;                 ar = mfma16(xf[kk], cf, ar); as = mfma16(xf[kk], sf, as); }
;             const int ka = 16 * i + lr; float tc, ts; sincospif(2.0f * (float)(b * ka) / (float)S, &ts, &tc);
;             const f32x4 re = ar * tc - as * ts, im = -(as * tc) - ar * ts;
;             bf16_t* op = A1 + (sbase + (size_t)ka * 128 + b) * 2048 + cb * 128 + 16 * w + 4 * lq;
;             u32x2 o; o.x = cvt_pk_bf16(re[0], re[1]); o.y = cvt_pk_bf16(re[2], re[3]); *(u32x2*)op = o;
;             o.x = cvt_pk_bf16(im[0], im[1]); o.y = cvt_pk_bf16(im[2], im[3]); *(u32x2*)(op + 1024) = o; }
	v_mfma_f32_16x16x32_bf16 v[52:55], v[14:17], v[52:55], 0
	s_waitcnt lgkmcnt(2)
	v_mfma_f32_16x16x32_bf16 v[56:59], v[14:17], v[56:59], 0
	s_waitcnt lgkmcnt(1)
	v_mfma_f32_16x16x32_bf16 v[52:55], v[10:13], v[60:63], v[52:55]
	s_waitcnt lgkmcnt(0)
	v_mfma_f32_16x16x32_bf16 v[56:59], v[10:13], v[64:67], v[56:59]
	ds_read_b128 v[60:63], v27 offset:128
	ds_read_b128 v[64:67], v27 offset:34944
	s_waitcnt lgkmcnt(1)
	v_mfma_f32_16x16x32_bf16 v[52:55], v[6:9], v[60:63], v[52:55]
	s_waitcnt lgkmcnt(0)
	v_mfma_f32_16x16x32_bf16 v[56:59], v[6:9], v[64:67], v[56:59]
	ds_read_b128 v[60:63], v27 offset:192
	ds_read_b128 v[64:67], v27 offset:35008
	s_waitcnt lgkmcnt(1)
	v_mfma_f32_16x16x32_bf16 v[52:55], v[2:5], v[60:63], v[52:55]
	v_lshl_add_u64 v[60:61], s[6:7], 0, v[28:29]
	v_lshlrev_b64 v[60:61], 12, v[60:61]
	v_lshl_add_u64 v[76:77], v[36:37], 0, v[60:61]
	s_waitcnt lgkmcnt(0)
	v_mfma_f32_16x16x32_bf16 v[56:59], v[2:5], v[64:67], v[56:59]
	ds_read_b128 v[60:63], v38
	ds_read_b128 v[64:67], v38 offset:34816
	ds_read_b128 v[68:71], v38 offset:64
	ds_read_b128 v[72:75], v38 offset:34880
	s_waitcnt lgkmcnt(3)
	v_mfma_f32_16x16x32_bf16 v[60:63], v[14:17], v[60:63], 0
	s_waitcnt lgkmcnt(2)
	v_mfma_f32_16x16x32_bf16 v[64:67], v[14:17], v[64:67], 0
	s_waitcnt lgkmcnt(1)
	v_mfma_f32_16x16x32_bf16 v[60:63], v[10:13], v[68:71], v[60:63]
	s_waitcnt lgkmcnt(0)
	v_mfma_f32_16x16x32_bf16 v[64:67], v[10:13], v[72:75], v[64:67]
	ds_read_b128 v[68:71], v38 offset:128
	ds_read_b128 v[72:75], v38 offset:34944
	s_waitcnt lgkmcnt(1)
	v_mfma_f32_16x16x32_bf16 v[60:63], v[6:9], v[68:71], v[60:63]
	s_waitcnt lgkmcnt(0)
	v_mfma_f32_16x16x32_bf16 v[64:67], v[6:9], v[72:75], v[64:67]
	ds_read_b128 v[68:71], v38 offset:192
	ds_read_b128 v[72:75], v38 offset:35008
	s_waitcnt lgkmcnt(1)
	v_mfma_f32_16x16x32_bf16 v[60:63], v[2:5], v[68:71], v[60:63]
	v_cvt_f32_u32_e32 v69, v79
	v_cvt_f32_u32_e32 v68, v78
	v_pk_mul_f32 v[68:69], v[68:69], s[14:15] op_sel_hi:[1,0]
	s_nop 0
	v_pk_mul_f32 v[70:71], v[68:69], 0.5 op_sel_hi:[1,0]
	s_waitcnt lgkmcnt(0)
	v_mfma_f32_16x16x32_bf16 v[64:67], v[2:5], v[72:75], v[64:67]
	v_fract_f32_e32 v72, v71
	v_add_f32_e32 v72, v72, v72
	v_cmp_neq_f32_e32 vcc, s10, v71
	s_nop 1
	v_cndmask_b32_e32 v71, 0, v72, vcc
	v_cmp_lt_f32_e32 vcc, 1.0, v69
	s_nop 1
	v_cndmask_b32_e32 v71, v69, v71, vcc
	v_add_f32_e32 v72, v71, v71
	v_rndne_f32_e32 v72, v72
	v_fmac_f32_e32 v71, -0.5, v72
	v_mul_f32_e32 v73, v71, v71
	v_fmamk_f32 v74, v73, 0x3e75aa41, v82
	v_fmaak_f32 v74, v73, v74, 0x40234736
	v_fmaak_f32 v74, v73, v74, 0xc0a55e0e
	v_mul_f32_e32 v75, v71, v73
	v_mul_f32_e32 v74, v75, v74
	v_cvt_i32_f32_e32 v72, v72
	v_fmac_f32_e32 v74, 0x40490fdb, v71
	v_fmamk_f32 v71, v73, 0x3d4be544, v83
	v_fmaak_f32 v71, v73, v71, 0xbfaad1da
	v_fmaak_f32 v71, v73, v71, 0x4081e0d3
	v_fmaak_f32 v71, v73, v71, 0xc09de9e6
	v_fma_f32 v71, v73, v71, 1.0
	v_lshlrev_b32_e32 v73, 30, v72
	v_and_b32_e32 v72, 1, v72
	v_cmp_eq_u32_e32 vcc, 0, v72
	s_nop 1
	v_cndmask_b32_e32 v72, v71, v74, vcc
	v_bitop3_b32 v75, v72, v73, s11 bitop3:0x78
	v_xor_b32_e32 v72, 0x80000000, v74
	v_cndmask_b32_e32 v71, v72, v71, vcc
	v_cmp_lg_f32_e32 vcc, s10, v69
	v_bitop3_b32 v71, v71, v73, s11 bitop3:0x78
	s_nop 0
	v_cndmask_b32_e32 v74, v84, v75, vcc
	v_cndmask_b32_e32 v72, v84, v71, vcc
	v_pk_mul_f32 v[78:79], v[74:75], v[56:57] op_sel_hi:[0,1]
	v_pk_mul_f32 v[80:81], v[74:75], v[58:59] op_sel_hi:[0,1]
	v_pk_fma_f32 v[80:81], v[72:73], v[54:55], v[80:81] op_sel_hi:[0,1,1] neg_lo:[0,0,1] neg_hi:[0,0,1]
	v_pk_fma_f32 v[78:79], v[72:73], v[52:53], v[78:79] op_sel_hi:[0,1,1] neg_lo:[0,0,1] neg_hi:[0,0,1]
	v_pk_mul_f32 v[52:53], v[74:75], v[52:53] op_sel_hi:[0,1]
	v_pk_mul_f32 v[54:55], v[74:75], v[54:55] op_sel_hi:[0,1]
	v_pk_fma_f32 v[54:55], v[58:59], v[72:73], v[54:55] op_sel_hi:[1,0,1] neg_lo:[0,1,1] neg_hi:[0,1,1]
	v_pk_fma_f32 v[52:53], v[56:57], v[72:73], v[52:53] op_sel_hi:[1,0,1] neg_lo:[0,1,1] neg_hi:[0,1,1]
	v_cmp_neq_f32_e32 vcc, s10, v70
	v_cvt_pk_bf16_f32 v52, v52, v53
	v_cvt_pk_bf16_f32 v53, v54, v55
	global_store_dwordx2 v[76:77], v[52:53], off offset:2048
	v_fract_f32_e32 v52, v70
	v_add_f32_e32 v52, v52, v52
	v_cndmask_b32_e32 v52, 0, v52, vcc
	v_cmp_lt_f32_e32 vcc, 1.0, v68
	v_cvt_pk_bf16_f32 v56, v78, v79
	v_cvt_pk_bf16_f32 v57, v80, v81
	v_cndmask_b32_e32 v52, v68, v52, vcc
	v_add_f32_e32 v53, v52, v52
	v_rndne_f32_e32 v53, v53
	v_fmac_f32_e32 v52, -0.5, v53
	v_mul_f32_e32 v54, v52, v52
	v_fmamk_f32 v55, v54, 0x3e75aa41, v82
	v_fmaak_f32 v55, v54, v55, 0x40234736
	global_store_dwordx2 v[76:77], v[56:57], off
	v_fmaak_f32 v55, v54, v55, 0xc0a55e0e
	v_mul_f32_e32 v56, v52, v54
	v_mul_f32_e32 v55, v56, v55
	v_cvt_i32_f32_e32 v53, v53
	v_fmac_f32_e32 v55, 0x40490fdb, v52
	v_fmamk_f32 v52, v54, 0x3d4be544, v83
	v_fmaak_f32 v52, v54, v52, 0xbfaad1da
	v_fmaak_f32 v52, v54, v52, 0x4081e0d3
	v_fmaak_f32 v52, v54, v52, 0xc09de9e6
	v_fma_f32 v52, v54, v52, 1.0
	v_lshlrev_b32_e32 v54, 30, v53
	v_and_b32_e32 v53, 1, v53
	v_cmp_eq_u32_e32 vcc, 0, v53
	v_mul_u32_u24_e32 v74, s21, v47
	v_mul_u32_u24_e32 v75, s21, v48
	v_cndmask_b32_e32 v53, v52, v55, vcc
	v_xor_b32_e32 v55, 0x80000000, v55
	v_bitop3_b32 v53, v53, v54, s11 bitop3:0x78
	v_cndmask_b32_e32 v52, v55, v52, vcc
	v_cmp_lg_f32_e32 vcc, s10, v68
	v_bitop3_b32 v52, v52, v54, s11 bitop3:0x78
	s_nop 0
	v_cndmask_b32_e32 v54, v84, v53, vcc
	v_cndmask_b32_e32 v52, v84, v52, vcc
	v_pk_mul_f32 v[56:57], v[54:55], v[64:65] op_sel_hi:[0,1]
	v_pk_mul_f32 v[58:59], v[54:55], v[66:67] op_sel_hi:[0,1]
	v_pk_fma_f32 v[56:57], v[52:53], v[60:61], v[56:57] op_sel_hi:[0,1,1] neg_lo:[0,0,1] neg_hi:[0,0,1]
	v_pk_mul_f32 v[60:61], v[54:55], v[60:61] op_sel_hi:[0,1]
	v_pk_mul_f32 v[54:55], v[54:55], v[62:63] op_sel_hi:[0,1]
	v_pk_fma_f32 v[58:59], v[52:53], v[62:63], v[58:59] op_sel_hi:[0,1,1] neg_lo:[0,0,1] neg_hi:[0,0,1]
	v_pk_fma_f32 v[54:55], v[66:67], v[52:53], v[54:55] op_sel_hi:[1,0,1] neg_lo:[0,1,1] neg_hi:[0,1,1]
	v_pk_fma_f32 v[52:53], v[64:65], v[52:53], v[60:61] op_sel_hi:[1,0,1] neg_lo:[0,1,1] neg_hi:[0,1,1]
	v_lshl_add_u64 v[60:61], s[6:7], 0, v[30:31]
	v_lshlrev_b64 v[60:61], 12, v[60:61]
	v_lshl_add_u64 v[60:61], v[36:37], 0, v[60:61]
	v_cvt_pk_bf16_f32 v56, v56, v57
	v_cvt_pk_bf16_f32 v57, v58, v59
	v_cvt_pk_bf16_f32 v52, v52, v53
	v_cvt_pk_bf16_f32 v53, v54, v55
	global_store_dwordx2 v[60:61], v[56:57], off
	global_store_dwordx2 v[60:61], v[52:53], off offset:2048
	ds_read_b128 v[52:55], v39
	ds_read_b128 v[56:59], v39 offset:34816
	ds_read_b128 v[60:63], v39 offset:64
	ds_read_b128 v[64:67], v39 offset:34880
	s_waitcnt lgkmcnt(3)
; __device__ __forceinline__ unsigned cvt_pk_bf16(float lo, float hi) { const f2_t v = {lo, hi}; const bf2_t b = __builtin_convertvector(v, bf2_t); return __builtin_bit_cast(unsigned, b); }
; __device__ __forceinline__ f32x4 mfma16(bf16x8 a, bf16x8 b, f32x4 c) { return __builtin_amdgcn_mfma_f32_16x16x32_bf16(a, b, c, 0, 0, 0); }
; template <int N1> __device__ void fft1_units(int wv, const Params& p, unsigned char* lds, int seq_lo, int nseq, int part, int nparts) {
;     ...
;         for (int i = 0; i < NB; ++i) { f32x4 ar = {0, 0, 0, 0}, as = {0, 0, 0, 0};
; #pragma unroll
;             for (int kk = 0; kk < NK; ++kk) { const bf16x8 cf = *(const bf16x8*)(CT + (16 * i + lr) * PW + 32 * kk + 8 * lq), sf = *(const bf16x8*)(ST + (16 * i + lr) * PW + 32 * kk + 8 * lq);
;                 ar = mfma16(xf[kk], cf, ar); as = mfma16(xf[kk], sf, as); }
;             const int ka = 16 * i + lr; float tc, ts; sincospif(2.0f * (float)(b * ka) / (float)S, &ts, &tc);
;             const f32x4 re = ar * tc - as * ts, im = -(as * tc) - ar * ts;
;             bf16_t* op = A1 + (sbase + (size_t)ka * 128 + b) * 2048 + cb * 128 + 16 * w + 4 * lq;
;             u32x2 o; o.x = cvt_pk_bf16(re[0], re[1]); o.y = cvt_pk_bf16(re[2], re[3]); *(u32x2*)op = o;
;             o.x = cvt_pk_bf16(im[0], im[1]); o.y = cvt_pk_bf16(im[2], im[3]); *(u32x2*)(op + 1024) = o; }
;         __syncthreads();
;     }
	v_mfma_f32_16x16x32_bf16 v[52:55], v[14:17], v[52:55], 0
	s_waitcnt lgkmcnt(2)
	v_mfma_f32_16x16x32_bf16 v[56:59], v[14:17], v[56:59], 0
	s_waitcnt lgkmcnt(1)
	v_mfma_f32_16x16x32_bf16 v[52:55], v[10:13], v[60:63], v[52:55]
	s_waitcnt lgkmcnt(0)
	v_mfma_f32_16x16x32_bf16 v[56:59], v[10:13], v[64:67], v[56:59]
	ds_read_b128 v[60:63], v39 offset:128
	ds_read_b128 v[64:67], v39 offset:34944
	s_waitcnt lgkmcnt(1)
	v_mfma_f32_16x16x32_bf16 v[52:55], v[6:9], v[60:63], v[52:55]
	s_waitcnt lgkmcnt(0)
	v_mfma_f32_16x16x32_bf16 v[56:59], v[6:9], v[64:67], v[56:59]
	ds_read_b128 v[60:63], v39 offset:192
	ds_read_b128 v[64:67], v39 offset:35008
	s_waitcnt lgkmcnt(1)
	v_mfma_f32_16x16x32_bf16 v[52:55], v[2:5], v[60:63], v[52:55]
	v_lshl_add_u64 v[60:61], s[6:7], 0, v[32:33]
	v_lshlrev_b64 v[60:61], 12, v[60:61]
	v_lshl_add_u64 v[72:73], v[36:37], 0, v[60:61]
	s_waitcnt lgkmcnt(0)
	v_mfma_f32_16x16x32_bf16 v[56:59], v[2:5], v[64:67], v[56:59]
	ds_read_b128 v[60:63], v40
	ds_read_b128 v[64:67], v40 offset:34816
	s_waitcnt lgkmcnt(1)
	v_mfma_f32_16x16x32_bf16 v[60:63], v[14:17], v[60:63], 0
	s_waitcnt lgkmcnt(0)
	v_mfma_f32_16x16x32_bf16 v[14:17], v[14:17], v[64:67], 0
	ds_read_b128 v[64:67], v40 offset:64
	ds_read_b128 v[68:71], v40 offset:34880
	s_waitcnt lgkmcnt(1)
	v_mfma_f32_16x16x32_bf16 v[60:63], v[10:13], v[64:67], v[60:63]
	s_waitcnt lgkmcnt(0)
	v_mfma_f32_16x16x32_bf16 v[10:13], v[10:13], v[68:71], v[14:17]
	s_nop 2
	ds_read_b128 v[14:17], v40 offset:128
	ds_read_b128 v[64:67], v40 offset:34944
	s_waitcnt lgkmcnt(1)
	v_mfma_f32_16x16x32_bf16 v[14:17], v[6:9], v[14:17], v[60:63]
	s_waitcnt lgkmcnt(0)
	v_mfma_f32_16x16x32_bf16 v[6:9], v[6:9], v[64:67], v[10:13]
	s_nop 2
	ds_read_b128 v[10:13], v40 offset:192
	ds_read_b128 v[60:63], v40 offset:35008
	s_waitcnt lgkmcnt(1)
	v_mfma_f32_16x16x32_bf16 v[10:13], v[2:5], v[10:13], v[14:17]
	s_waitcnt lgkmcnt(0)
	v_mfma_f32_16x16x32_bf16 v[2:5], v[2:5], v[60:63], v[6:9]
	s_nop 2
	v_cvt_f32_u32_e32 v7, v75
	v_cvt_f32_u32_e32 v6, v74
	v_pk_mul_f32 v[6:7], v[6:7], s[14:15] op_sel_hi:[1,0]
	s_nop 0
	v_pk_mul_f32 v[8:9], v[6:7], 0.5 op_sel_hi:[1,0]
	s_nop 0
	v_fract_f32_e32 v14, v9
	v_add_f32_e32 v14, v14, v14
	v_cmp_neq_f32_e32 vcc, s10, v9
	s_nop 1
	v_cndmask_b32_e32 v9, 0, v14, vcc
	v_cmp_lt_f32_e32 vcc, 1.0, v7
	s_nop 1
	v_cndmask_b32_e32 v9, v7, v9, vcc
	v_add_f32_e32 v14, v9, v9
	v_rndne_f32_e32 v14, v14
	v_fmac_f32_e32 v9, -0.5, v14
	v_mul_f32_e32 v15, v9, v9
	v_fmamk_f32 v16, v15, 0x3e75aa41, v82
	v_fmaak_f32 v16, v15, v16, 0x40234736
	v_fmaak_f32 v16, v15, v16, 0xc0a55e0e
	v_mul_f32_e32 v17, v9, v15
	v_mul_f32_e32 v16, v17, v16
	v_cvt_i32_f32_e32 v14, v14
	v_fmac_f32_e32 v16, 0x40490fdb, v9
	v_fmamk_f32 v9, v15, 0x3d4be544, v83
	v_fmaak_f32 v9, v15, v9, 0xbfaad1da
	v_fmaak_f32 v9, v15, v9, 0x4081e0d3
	v_fmaak_f32 v9, v15, v9, 0xc09de9e6
	v_fma_f32 v9, v15, v9, 1.0
	v_lshlrev_b32_e32 v15, 30, v14
	v_and_b32_e32 v14, 1, v14
	v_cmp_eq_u32_e32 vcc, 0, v14
	s_nop 1
	v_cndmask_b32_e32 v14, v9, v16, vcc
	v_bitop3_b32 v17, v14, v15, s11 bitop3:0x78
	v_xor_b32_e32 v14, 0x80000000, v16
	v_cndmask_b32_e32 v9, v14, v9, vcc
	v_bitop3_b32 v9, v9, v15, s11 bitop3:0x78
	v_cmp_lg_f32_e32 vcc, s10, v7
	v_fract_f32_e32 v7, v8
	v_add_f32_e32 v7, v7, v7
	v_cndmask_b32_e32 v14, v84, v9, vcc
	v_cndmask_b32_e32 v16, v84, v17, vcc
	v_cmp_neq_f32_e32 vcc, s10, v8
	v_pk_mul_f32 v[60:61], v[16:17], v[56:57] op_sel_hi:[0,1]
	v_pk_mul_f32 v[62:63], v[16:17], v[58:59] op_sel_hi:[0,1]
	v_cndmask_b32_e32 v7, 0, v7, vcc
	v_cmp_lt_f32_e32 vcc, 1.0, v6
	v_pk_fma_f32 v[60:61], v[14:15], v[52:53], v[60:61] op_sel_hi:[0,1,1] neg_lo:[0,0,1] neg_hi:[0,0,1]
	v_pk_mul_f32 v[52:53], v[16:17], v[52:53] op_sel_hi:[0,1]
	v_cndmask_b32_e32 v7, v6, v7, vcc
	v_add_f32_e32 v8, v7, v7
	v_pk_mul_f32 v[16:17], v[16:17], v[54:55] op_sel_hi:[0,1]
	v_rndne_f32_e32 v8, v8
	v_pk_fma_f32 v[62:63], v[14:15], v[54:55], v[62:63] op_sel_hi:[0,1,1] neg_lo:[0,0,1] neg_hi:[0,0,1]
	v_pk_fma_f32 v[16:17], v[58:59], v[14:15], v[16:17] op_sel_hi:[1,0,1] neg_lo:[0,1,1] neg_hi:[0,1,1]
	v_pk_fma_f32 v[14:15], v[56:57], v[14:15], v[52:53] op_sel_hi:[1,0,1] neg_lo:[0,1,1] neg_hi:[0,1,1]
	v_fmac_f32_e32 v7, -0.5, v8
	v_cvt_pk_bf16_f32 v14, v14, v15
	v_cvt_pk_bf16_f32 v15, v16, v17
	v_mul_f32_e32 v9, v7, v7
	global_store_dwordx2 v[72:73], v[14:15], off offset:2048
	v_fmamk_f32 v14, v9, 0x3e75aa41, v82
	v_fmaak_f32 v14, v9, v14, 0x40234736
	v_fmaak_f32 v14, v9, v14, 0xc0a55e0e
	v_mul_f32_e32 v15, v7, v9
	v_mul_f32_e32 v14, v15, v14
	v_cvt_i32_f32_e32 v8, v8
	v_fmac_f32_e32 v14, 0x40490fdb, v7
	v_fmamk_f32 v7, v9, 0x3d4be544, v83
	v_fmaak_f32 v7, v9, v7, 0xbfaad1da
	v_fmaak_f32 v7, v9, v7, 0x4081e0d3
	v_fmaak_f32 v7, v9, v7, 0xc09de9e6
	v_fma_f32 v7, v9, v7, 1.0
	v_lshlrev_b32_e32 v9, 30, v8
	v_and_b32_e32 v8, 1, v8
	v_cmp_eq_u32_e32 vcc, 0, v8
	v_cvt_pk_bf16_f32 v52, v60, v61
	v_cvt_pk_bf16_f32 v53, v62, v63
	v_cndmask_b32_e32 v8, v7, v14, vcc
	v_xor_b32_e32 v14, 0x80000000, v14
	v_bitop3_b32 v8, v8, v9, s11 bitop3:0x78
	v_cndmask_b32_e32 v7, v14, v7, vcc
	v_cmp_lg_f32_e32 vcc, s10, v6
	v_bitop3_b32 v7, v7, v9, s11 bitop3:0x78
	global_store_dwordx2 v[72:73], v[52:53], off
	v_cndmask_b32_e32 v8, v84, v8, vcc
	v_cndmask_b32_e32 v6, v84, v7, vcc
	v_pk_mul_f32 v[14:15], v[8:9], v[2:3] op_sel_hi:[0,1]
	v_pk_mul_f32 v[16:17], v[8:9], v[4:5] op_sel_hi:[0,1]
	v_pk_fma_f32 v[14:15], v[6:7], v[10:11], v[14:15] op_sel_hi:[0,1,1] neg_lo:[0,0,1] neg_hi:[0,0,1]
	v_pk_mul_f32 v[10:11], v[8:9], v[10:11] op_sel_hi:[0,1]
	v_pk_mul_f32 v[8:9], v[8:9], v[12:13] op_sel_hi:[0,1]
	v_pk_fma_f32 v[16:17], v[6:7], v[12:13], v[16:17] op_sel_hi:[0,1,1] neg_lo:[0,0,1] neg_hi:[0,0,1]
	v_pk_fma_f32 v[4:5], v[4:5], v[6:7], v[8:9] op_sel_hi:[1,0,1] neg_lo:[0,1,1] neg_hi:[0,1,1]
	v_pk_fma_f32 v[2:3], v[2:3], v[6:7], v[10:11] op_sel_hi:[1,0,1] neg_lo:[0,1,1] neg_hi:[0,1,1]
	v_lshl_add_u64 v[6:7], s[6:7], 0, v[34:35]
	v_lshlrev_b64 v[6:7], 12, v[6:7]
	v_lshl_add_u64 v[6:7], v[36:37], 0, v[6:7]
	v_cvt_pk_bf16_f32 v8, v14, v15
	v_cvt_pk_bf16_f32 v9, v16, v17
	v_cvt_pk_bf16_f32 v2, v2, v3
	v_cvt_pk_bf16_f32 v3, v4, v5
	global_store_dwordx2 v[6:7], v[8:9], off
	global_store_dwordx2 v[6:7], v[2:3], off offset:2048
	s_barrier
	s_cbranch_scc1 .LBB0_319
; template <int N1> __device__ void fft1_units(int wv, const Params& p, unsigned char* lds, int seq_lo, int nseq, int part, int nparts) {
;     ...
;     for (int unit = part; unit < nunits; unit += nparts) {
;         const int sq = unit / 1024, b = (unit >> 3) & 127, cb = unit & 7;
;         const int seq = seq_lo + sq; const size_t sbase = (size_t)seq * 8192;
;         for (int idx = tid; idx < N1 * 16; idx += NTHR) { const int a = idx % N1, c8 = (idx / N1) * 8;
;             const bf16x8 v = *(const bf16x8*)(z + (sbase + 128 * a + b) * DM + cb * 128 + c8);
; #pragma unroll
;             for (int e = 0; e < 8; ++e) XT[(c8 + e) * PW + a] = (bf16_t)v[e]; }
;         __syncthreads();
.LBB0_316:
	s_ashr_i32 s6, s20, 31
	s_lshr_b32 s6, s6, 22
	s_add_i32 s6, s20, s6
	s_ashr_i32 s6, s6, 10
	s_ashr_i32 s7, s6, 31
	s_bfe_u32 s21, s20, 0x70003
	s_lshl_b64 s[6:7], s[6:7], 13
	s_or_b32 s6, s6, s21
	s_add_u32 s6, s6, 0x4000
	s_addc_u32 s7, s7, 0
	s_lshl_b32 s10, s20, 7
	s_and_b32 s22, s10, 0x380
	s_mov_b64 s[10:11], exec
	s_movk_i32 s36, 0x5ff
	s_lshl_b32 s14, s22, 1
	s_add_u32 s14, s76, s14
	s_addc_u32 s15, s77, 0
	s_lshl_b64 s[16:17], s[6:7], 11
	s_add_u32 s14, s14, s16
	s_addc_u32 s15, s15, s17
	v_lshl_add_u64 v[204:205], s[14:15], 0, v[200:201]
	s_mov_b64 s[16:17], 0x800000
	global_load_dwordx4 v[206:209], v[204:205], off
	v_lshl_add_u64 v[204:205], v[204:205], 0, s[16:17]
	global_load_dwordx4 v[210:213], v[204:205], off
	v_lshl_add_u64 v[204:205], v[204:205], 0, s[16:17]
	global_load_dwordx4 v[214:217], v[204:205], off
	v_lshl_add_u64 v[204:205], v[204:205], 0, s[16:17]
	global_load_dwordx4 v[218:221], v[204:205], off
	s_waitcnt vmcnt(3)
	ds_write_b128 v202, v[206:209]
	s_waitcnt vmcnt(2)
	ds_write_b128 v202, v[210:213] offset:8192
	s_waitcnt vmcnt(1)
	ds_write_b128 v202, v[214:217] offset:16384
	s_waitcnt vmcnt(0)
	ds_write_b128 v202, v[218:221] offset:24576
	s_branch .LBB0_315

; __device__ __forceinline__ int otid(int wv) { int t; asm volatile("v_mbcnt_lo_u32_b32 %0, -1, 0\n\tv_mbcnt_hi_u32_b32 %0, -1, %0\n\tv_lshl_add_u32 %0, %1, 6, %0" : "=&v"(t) : "s"(wv)); return t; }
; template <int N1> __device__ void fft1_units(int wv, const Params& p, unsigned char* lds, int seq_lo, int nseq, int part, int nparts) {
;     const int tid = otid(wv), lane = tid & 63, w = __builtin_amdgcn_readfirstlane(tid >> 6), lr = lane & 15, lq = lane >> 4;
;     constexpr int PW = N1 + 8, NB = N1 / 16, NK = N1 / 32; constexpr int S = N1 * 128;
;     const bf16_t* z = (const bf16_t*)(p.ws + WS_BIG1); bf16_t* A1 = (bf16_t*)(p.ws + WS_BIG2);
;     const bf16_t* ctg = (const bf16_t*)(p.ws + WS_TAB + (N1 == 64 ? TAB_CT64 : TAB_CT128)); const bf16_t* stg = (const bf16_t*)(p.ws + WS_TAB + (N1 == 64 ? TAB_ST64 : TAB_ST128));
;     bf16_t* CT = (bf16_t*)lds; bf16_t* ST = CT + N1 * PW; bf16_t* XT = ST + N1 * PW;
;     for (int idx = tid; idx < N1 * N1 / 8; idx += NTHR) { const int r = idx / (N1 / 8), c8 = (idx % (N1 / 8)) * 8;
;         *(bf16x8*)(CT + r * PW + c8) = *(const bf16x8*)(ctg + r * N1 + c8); *(bf16x8*)(ST + r * PW + c8) = *(const bf16x8*)(stg + r * N1 + c8); }
;     __syncthreads();
;     const int nunits = nseq * 128 * 8;
;     for (int unit = part; unit < nunits; unit += nparts) {
;         const int sq = unit / 1024, b = (unit >> 3) & 127, cb = unit & 7;
;         const int seq = seq_lo + sq; const size_t sbase = (size_t)seq * 8192;
;         for (int idx = tid; idx < N1 * 16; idx += NTHR) { const int a = idx % N1, c8 = (idx / N1) * 8;
;             const bf16x8 v = *(const bf16x8*)(z + (sbase + 128 * a + b) * DM + cb * 128 + c8);
; #pragma unroll
;             for (int e = 0; e < 8; ++e) XT[(c8 + e) * PW + a] = (bf16_t)v[e]; }
;         __syncthreads();
;         bf16x8 xf[NK];
; #pragma unroll
;         for (int kk = 0; kk < NK; ++kk) xf[kk] = *(const bf16x8*)(XT + (16 * w + lr) * PW + 32 * kk + 8 * lq);
; #pragma unroll
;         for (int i = 0; i < NB; ++i) { f32x4 ar = {0, 0, 0, 0}, as = {0, 0, 0, 0};
; #pragma unroll
;             for (int kk = 0; kk < NK; ++kk) { const bf16x8 cf = *(const bf16x8*)(CT + (16 * i + lr) * PW + 32 * kk + 8 * lq), sf = *(const bf16x8*)(ST + (16 * i + lr) * PW + 32 * kk + 8 * lq);
;                 ar = mfma16(xf[kk], cf, ar); as = mfma16(xf[kk], sf, as); }
.LBB0_324:
	s_or_b64 exec, exec, s[0:1]
	v_readlane_b32 s0, v254, 9
	v_readlane_b32 s1, v254, 10
	s_andn2_b64 vcc, exec, s[0:1]
	s_waitcnt lgkmcnt(0)
	s_barrier
	s_cbranch_vccnz .LBB0_333
	s_movk_i32 s0, 0x3ff
	s_ashr_i32 s1, s10, 2
	v_cmp_lt_i32_e32 vcc, s0, v1
	s_and_b32 s0, s1, -16
	v_bfi_b32 v3, -16, s1, v1
	s_movk_i32 s1, 0x90
	v_mul_lo_u32 v3, v3, s1
	s_ashr_i32 s1, s0, 31
	s_lshl_b64 s[0:1], s[0:1], 1
	v_readlane_b32 s6, v254, 13
	v_and_b32_e32 v4, 15, v1
	v_bfe_u32 v2, v1, 4, 2
	v_readlane_b32 s7, v254, 14
	s_add_u32 s0, s6, s0
	v_add_u32_e32 v5, 0, v3
	v_lshlrev_b32_e32 v6, 4, v2
	v_lshlrev_b32_e32 v2, 3, v2
	s_addc_u32 s1, s7, s1
	v_mov_b32_e32 v3, v0
	v_or_b32_e32 v18, 32, v4
	v_or_b32_e32 v17, 48, v4
	v_add_u32_e32 v7, 0, v6
	v_lshl_add_u64 v[2:3], s[0:1], 0, v[2:3]
	v_mul_u32_u24_e32 v8, 0x48, v4
	v_or_b32_e32 v15, 16, v4
	v_mul_u32_u24_e32 v11, 0x48, v18
	v_mul_u32_u24_e32 v13, 0x48, v17
	v_readlane_b32 s0, v254, 58
	v_lshl_add_u32 v8, v8, 1, v7
	v_lshlrev_b32_e32 v9, 7, v4
	v_lshlrev_b32_e32 v10, 7, v15
	v_lshl_add_u32 v11, v11, 1, v7
	v_lshlrev_b32_e32 v12, 7, v18
	v_lshl_add_u32 v13, v13, 1, v7
	v_lshlrev_b32_e32 v14, 7, v17
	v_lshlrev_b32_e32 v15, 1, v15
	v_lshlrev_b32_e32 v16, 1, v4
	v_lshlrev_b32_e32 v17, 1, v17
	v_lshlrev_b32_e32 v18, 1, v18
	v_lshlrev_b32_e32 v19, 7, v1
	v_lshl_add_u32 v20, v1, 1, s0
	v_add_u32_e32 v21, v5, v6
	s_mov_b32 s22, s2
	v_mbcnt_lo_u32_b32 v224, -1, 0
	v_mbcnt_hi_u32_b32 v224, -1, v224
	v_lshl_add_u32 v225, s33, 6, v224
	v_lshrrev_b32_e32 v226, 4, v225
	v_and_b32_e32 v227, 15, v225
	v_and_b32_e32 v228, 3, v226
	v_lshlrev_b32_e32 v228, 2, v228
	v_bfe_u32 v229, v226, 2, 2
	v_or_b32_e32 v228, v228, v229
	v_xor_b32_e32 v228, v227, v228
	v_lshlrev_b32_e32 v228, 4, v228
	v_lshl_add_u32 v202, v226, 8, v228
	v_add_u32_e32 v202, 0x4800, v202
	v_lshlrev_b32_e32 v200, 18, v226
	v_lshl_add_u32 v200, v227, 4, v200
	v_mov_b32_e32 v201, 0
	v_bfe_u32 v226, v224, 2, 2
	v_and_b32_e32 v227, 3, v224
	v_lshrrev_b32_e32 v228, 4, v224
	v_lshl_add_u32 v229, v228, 3, v226
	v_lshlrev_b32_e32 v230, 2, v226
	v_lshlrev_b32_e32 v228, 1, v228
	v_and_b32_e32 v231, 3, v228
	v_or_b32_e32 v231, v230, v231
	v_add_u32_e32 v228, 1, v228
	v_and_b32_e32 v228, 3, v228
	v_or_b32_e32 v228, v230, v228
	s_lshl_b32 s14, s33, 1
	v_lshrrev_b32_e32 v230, 1, v227
	v_add_u32_e32 v230, s14, v230
	v_and_b32_e32 v227, 1, v227
	v_lshlrev_b32_e32 v227, 3, v227
	v_xor_b32_e32 v231, v230, v231
	v_lshl_add_u32 v231, v231, 4, v227
	v_lshl_add_u32 v222, v229, 8, v231
	v_add_u32_e32 v222, 0x4800, v222
	v_xor_b32_e32 v228, v230, v228
	v_lshl_add_u32 v228, v228, 4, v227
	v_add_u32_e32 v229, 4, v229
	v_lshl_add_u32 v223, v229, 8, v228
	v_add_u32_e32 v223, 0x4800, v223
	s_branch .LBB0_327
.LBB0_326:
	s_or_b64 exec, exec, s[10:11]
	s_waitcnt lgkmcnt(0)
	s_barrier
	ds_read_b64_tr_b16 v[22:23], v222
	ds_read_b64_tr_b16 v[24:25], v223
	ds_read_b128 v[26:29], v8
	ds_read_b64_tr_b16 v[30:31], v222 offset:8192
	ds_read_b64_tr_b16 v[32:33], v223 offset:8192
	ds_read_b128 v[34:37], v8 offset:64
	ds_read_b128 v[38:41], v8 offset:9216
	ds_read_b128 v[42:45], v8 offset:9280
	s_waitcnt lgkmcnt(4)
	v_mfma_f32_16x16x32_bf16 v[26:29], v[22:25], v[26:29], 0
	v_mul_u32_u24_e32 v54, s23, v15
	v_mul_u32_u24_e32 v55, s23, v16
	v_cvt_f32_u32_e32 v55, v55
	s_waitcnt lgkmcnt(1)
	v_mfma_f32_16x16x32_bf16 v[38:41], v[22:25], v[38:41], 0
	v_cvt_f32_u32_e32 v54, v54
	s_mov_b32 s14, 0x39000000
	v_or_b32_e32 v6, s23, v9
	v_mfma_f32_16x16x32_bf16 v[26:29], v[30:33], v[34:37], v[26:29]
	ds_read_b128 v[34:37], v8 offset:2304
	v_or_b32_e32 v6, s6, v6
	v_mov_b32_e32 v7, s7
	s_waitcnt lgkmcnt(1)
	v_mfma_f32_16x16x32_bf16 v[38:41], v[30:33], v[42:45], v[38:41]
	ds_read_b128 v[42:45], v8 offset:11520
	ds_read_b128 v[46:49], v8 offset:2368
	ds_read_b128 v[50:53], v8 offset:11584
	s_mov_b32 s7, 0x7f800000
	s_waitcnt lgkmcnt(3)
	v_mfma_f32_16x16x32_bf16 v[34:37], v[22:25], v[34:37], 0
	v_mov_b32_e32 v58, 0xbf1f24be
	v_mov_b32_e32 v59, 0x3e642e9d
	s_brev_b32 s10, 1
	s_waitcnt lgkmcnt(2)
	v_mfma_f32_16x16x32_bf16 v[42:45], v[22:25], v[42:45], 0
	v_mov_b32_e32 v60, 0x7fc00000
	v_lshl_add_u64 v[4:5], v[4:5], 1, v[2:3]
	s_add_i32 s22, s22, s93
	s_waitcnt lgkmcnt(1)
	v_mfma_f32_16x16x32_bf16 v[34:37], v[30:33], v[46:49], v[34:37]
	v_mul_f32_e64 v48, v54, s14
	v_mul_f32_e64 v49, v55, s14
	v_lshlrev_b64 v[46:47], 12, v[6:7]
	v_lshl_add_u64 v[46:47], v[4:5], 0, v[46:47]
	s_waitcnt lgkmcnt(0)
; __device__ __forceinline__ unsigned cvt_pk_bf16(float lo, float hi) { const f2_t v = {lo, hi}; const bf2_t b = __builtin_convertvector(v, bf2_t); return __builtin_bit_cast(unsigned, b); }
; __device__ __forceinline__ f32x4 mfma16(bf16x8 a, bf16x8 b, f32x4 c) { return __builtin_amdgcn_mfma_f32_16x16x32_bf16(a, b, c, 0, 0, 0); }
; template <int N1> __device__ void fft1_units(int wv, const Params& p, unsigned char* lds, int seq_lo, int nseq, int part, int nparts) {
;     ...
;         for (int i = 0; i < NB; ++i) { f32x4 ar = {0, 0, 0, 0}, as = {0, 0, 0, 0};
; #pragma unroll
;             for (int kk = 0; kk < NK; ++kk) { const bf16x8 cf = *(const bf16x8*)(CT + (16 * i + lr) * PW + 32 * kk + 8 * lq), sf = *(const bf16x8*)(ST + (16 * i + lr) * PW + 32 * kk + 8 * lq);
;                 ar = mfma16(xf[kk], cf, ar); as = mfma16(xf[kk], sf, as); }
;             const int ka = 16 * i + lr; float tc, ts; sincospif(2.0f * (float)(b * ka) / (float)S, &ts, &tc);
;             const f32x4 re = ar * tc - as * ts, im = -(as * tc) - ar * ts;
;             bf16_t* op = A1 + (sbase + (size_t)ka * 128 + b) * 2048 + cb * 128 + 16 * w + 4 * lq;
;             u32x2 o; o.x = cvt_pk_bf16(re[0], re[1]); o.y = cvt_pk_bf16(re[2], re[3]); *(u32x2*)op = o;
;             o.x = cvt_pk_bf16(im[0], im[1]); o.y = cvt_pk_bf16(im[2], im[3]); *(u32x2*)(op + 1024) = o; }
	v_mfma_f32_16x16x32_bf16 v[42:45], v[30:33], v[50:53], v[42:45]
	v_mul_f32_e64 v50, v48, 0.5
	v_mul_f32_e64 v51, v49, 0.5
	s_cmpk_gt_i32 s22, 0x7ff
	v_fract_f32_e32 v6, v51
	v_add_f32_e32 v6, v6, v6
	v_cmp_neq_f32_e64 s[0:1], s7, v51
	s_nop 1
	v_cndmask_b32_e64 v6, 0, v6, s[0:1]
	v_cmp_lt_f32_e64 s[0:1], 1.0, v49
	s_nop 1
	v_cndmask_b32_e64 v6, v49, v6, s[0:1]
	v_add_f32_e32 v51, v6, v6
	v_rndne_f32_e32 v51, v51
	v_fmac_f32_e32 v6, -0.5, v51
	v_mul_f32_e32 v52, v6, v6
	v_fmamk_f32 v53, v52, 0x3e75aa41, v58
	v_fmaak_f32 v53, v52, v53, 0x40234736
	v_fmaak_f32 v53, v52, v53, 0xc0a55e0e
	v_mul_f32_e32 v54, v6, v52
	v_mul_f32_e32 v53, v54, v53
	v_cvt_i32_f32_e32 v51, v51
	v_fmac_f32_e32 v53, 0x40490fdb, v6
	v_fmamk_f32 v6, v52, 0x3d4be544, v59
	v_fmaak_f32 v6, v52, v6, 0xbfaad1da
	v_fmaak_f32 v6, v52, v6, 0x4081e0d3
	v_fmaak_f32 v6, v52, v6, 0xc09de9e6
	v_fma_f32 v6, v52, v6, 1.0
	v_lshlrev_b32_e32 v52, 30, v51
	v_and_b32_e32 v51, 1, v51
	v_cmp_eq_u32_e64 s[0:1], 0, v51
	s_nop 1
	v_cndmask_b32_e64 v51, v6, v53, s[0:1]
	v_xor_b32_e32 v53, 0x80000000, v53
	v_bitop3_b32 v51, v51, v52, s10 bitop3:0x78
	v_cndmask_b32_e64 v6, v53, v6, s[0:1]
	v_cmp_lg_f32_e64 s[0:1], s7, v49
	v_bitop3_b32 v6, v6, v52, s10 bitop3:0x78
	s_nop 0
	v_cndmask_b32_e64 v52, v60, v51, s[0:1]
	v_cndmask_b32_e64 v6, v60, v6, s[0:1]
	v_pk_mul_f32 v[54:55], v[52:53], v[38:39] op_sel_hi:[0,1]
	v_pk_mul_f32 v[56:57], v[52:53], v[40:41] op_sel_hi:[0,1]
	v_pk_fma_f32 v[56:57], v[6:7], v[28:29], v[56:57] op_sel_hi:[0,1,1] neg_lo:[0,0,1] neg_hi:[0,0,1]
	v_pk_fma_f32 v[54:55], v[6:7], v[26:27], v[54:55] op_sel_hi:[0,1,1] neg_lo:[0,0,1] neg_hi:[0,0,1]
	v_pk_mul_f32 v[26:27], v[52:53], v[26:27] op_sel_hi:[0,1]
	v_pk_mul_f32 v[28:29], v[52:53], v[28:29] op_sel_hi:[0,1]
	v_pk_fma_f32 v[28:29], v[40:41], v[6:7], v[28:29] op_sel_hi:[1,0,1] neg_lo:[0,1,1] neg_hi:[0,1,1]
	v_pk_fma_f32 v[26:27], v[38:39], v[6:7], v[26:27] op_sel_hi:[1,0,1] neg_lo:[0,1,1] neg_hi:[0,1,1]
	v_fract_f32_e32 v6, v50
	v_add_f32_e32 v6, v6, v6
	v_cmp_neq_f32_e64 s[0:1], s7, v50
	v_cvt_pk_bf16_f32 v26, v26, v27
	v_cvt_pk_bf16_f32 v27, v28, v29
	v_cndmask_b32_e64 v6, 0, v6, s[0:1]
	v_cmp_lt_f32_e64 s[0:1], 1.0, v48
	global_store_dwordx2 v[46:47], v[26:27], off offset:2048
	v_cvt_pk_bf16_f32 v38, v54, v55
	v_cndmask_b32_e64 v6, v48, v6, s[0:1]
	v_add_f32_e32 v26, v6, v6
	v_rndne_f32_e32 v26, v26
	v_fmac_f32_e32 v6, -0.5, v26
	v_mul_f32_e32 v27, v6, v6
	v_fmamk_f32 v28, v27, 0x3e75aa41, v58
	v_fmaak_f32 v28, v27, v28, 0x40234736
	v_fmaak_f32 v28, v27, v28, 0xc0a55e0e
	v_mul_f32_e32 v29, v6, v27
	v_mul_f32_e32 v28, v29, v28
	v_cvt_i32_f32_e32 v26, v26
	v_fmac_f32_e32 v28, 0x40490fdb, v6
	v_fmamk_f32 v6, v27, 0x3d4be544, v59
	v_fmaak_f32 v6, v27, v6, 0xbfaad1da
	v_fmaak_f32 v6, v27, v6, 0x4081e0d3
	v_fmaak_f32 v6, v27, v6, 0xc09de9e6
	v_fma_f32 v6, v27, v6, 1.0
	v_lshlrev_b32_e32 v27, 30, v26
	v_and_b32_e32 v26, 1, v26
	v_cmp_eq_u32_e64 s[0:1], 0, v26
	v_cvt_pk_bf16_f32 v39, v56, v57
	global_store_dwordx2 v[46:47], v[38:39], off
	v_cndmask_b32_e64 v26, v6, v28, s[0:1]
	v_xor_b32_e32 v28, 0x80000000, v28
	v_bitop3_b32 v26, v26, v27, s10 bitop3:0x78
	v_cndmask_b32_e64 v6, v28, v6, s[0:1]
	v_cmp_lg_f32_e64 s[0:1], s7, v48
	v_bitop3_b32 v6, v6, v27, s10 bitop3:0x78
	s_nop 0
	v_cndmask_b32_e64 v26, v60, v26, s[0:1]
	v_cndmask_b32_e64 v6, v60, v6, s[0:1]
	v_pk_mul_f32 v[28:29], v[26:27], v[42:43] op_sel_hi:[0,1]
	v_pk_mul_f32 v[38:39], v[26:27], v[44:45] op_sel_hi:[0,1]
	v_pk_fma_f32 v[48:49], v[6:7], v[34:35], v[28:29] op_sel_hi:[0,1,1] neg_lo:[0,0,1] neg_hi:[0,0,1]
	v_pk_mul_f32 v[34:35], v[26:27], v[34:35] op_sel_hi:[0,1]
	v_pk_mul_f32 v[26:27], v[26:27], v[36:37] op_sel_hi:[0,1]
	v_pk_fma_f32 v[50:51], v[44:45], v[6:7], v[26:27] op_sel_hi:[1,0,1] neg_lo:[0,1,1] neg_hi:[0,1,1]
	ds_read_b128 v[26:29], v11
	v_pk_fma_f32 v[46:47], v[6:7], v[36:37], v[38:39] op_sel_hi:[0,1,1] neg_lo:[0,0,1] neg_hi:[0,0,1]
	v_pk_fma_f32 v[52:53], v[42:43], v[6:7], v[34:35] op_sel_hi:[1,0,1] neg_lo:[0,1,1] neg_hi:[0,1,1]
	ds_read_b128 v[34:37], v11 offset:9216
	ds_read_b128 v[38:41], v11 offset:64
	v_or_b32_e32 v6, s23, v10
	s_waitcnt lgkmcnt(2)
	v_mfma_f32_16x16x32_bf16 v[26:29], v[22:25], v[26:29], 0
	ds_read_b128 v[42:45], v11 offset:9280
	v_or_b32_e32 v6, s6, v6
	v_lshlrev_b64 v[54:55], 12, v[6:7]
	s_waitcnt lgkmcnt(2)
	v_mfma_f32_16x16x32_bf16 v[34:37], v[22:25], v[34:37], 0
	v_lshl_add_u64 v[54:55], v[4:5], 0, v[54:55]
	v_cvt_pk_bf16_f32 v48, v48, v49
	v_cvt_pk_bf16_f32 v49, v46, v47
	s_waitcnt lgkmcnt(1)
	v_mfma_f32_16x16x32_bf16 v[26:29], v[30:33], v[38:41], v[26:29]
	global_store_dwordx2 v[54:55], v[48:49], off
	ds_read_b128 v[38:41], v13
	v_cvt_pk_bf16_f32 v52, v52, v53
	s_waitcnt lgkmcnt(1)
	v_mfma_f32_16x16x32_bf16 v[34:37], v[30:33], v[42:45], v[34:37]
	ds_read_b128 v[42:45], v13 offset:9216
	ds_read_b128 v[46:49], v13 offset:64
	v_cvt_pk_bf16_f32 v53, v50, v51
	global_store_dwordx2 v[54:55], v[52:53], off offset:2048
	s_waitcnt lgkmcnt(2)
	v_mfma_f32_16x16x32_bf16 v[38:41], v[22:25], v[38:41], 0
	v_mul_u32_u24_e32 v54, s23, v17
	ds_read_b128 v[50:53], v13 offset:9280
	v_or_b32_e32 v6, s23, v12
	s_waitcnt lgkmcnt(2)
	v_mfma_f32_16x16x32_bf16 v[22:25], v[22:25], v[42:45], 0
	v_mul_u32_u24_e32 v42, s23, v18
	v_cvt_f32_u32_e32 v43, v42
	v_cvt_f32_u32_e32 v42, v54
	s_waitcnt lgkmcnt(1)
; __device__ __forceinline__ unsigned cvt_pk_bf16(float lo, float hi) { const f2_t v = {lo, hi}; const bf2_t b = __builtin_convertvector(v, bf2_t); return __builtin_bit_cast(unsigned, b); }
; __device__ __forceinline__ f32x4 mfma16(bf16x8 a, bf16x8 b, f32x4 c) { return __builtin_amdgcn_mfma_f32_16x16x32_bf16(a, b, c, 0, 0, 0); }
; template <int N1> __device__ void fft1_units(int wv, const Params& p, unsigned char* lds, int seq_lo, int nseq, int part, int nparts) {
;     ...
;     for (int unit = part; unit < nunits; unit += nparts) {
;         const int sq = unit / 1024, b = (unit >> 3) & 127, cb = unit & 7;
;         const int seq = seq_lo + sq; const size_t sbase = (size_t)seq * 8192;
;         for (int idx = tid; idx < N1 * 16; idx += NTHR) { const int a = idx % N1, c8 = (idx / N1) * 8;
;             const bf16x8 v = *(const bf16x8*)(z + (sbase + 128 * a + b) * DM + cb * 128 + c8);
; #pragma unroll
;             for (int e = 0; e < 8; ++e) XT[(c8 + e) * PW + a] = (bf16_t)v[e]; }
;         __syncthreads();
;     ...
;         for (int i = 0; i < NB; ++i) { f32x4 ar = {0, 0, 0, 0}, as = {0, 0, 0, 0};
; #pragma unroll
;             for (int kk = 0; kk < NK; ++kk) { const bf16x8 cf = *(const bf16x8*)(CT + (16 * i + lr) * PW + 32 * kk + 8 * lq), sf = *(const bf16x8*)(ST + (16 * i + lr) * PW + 32 * kk + 8 * lq);
;                 ar = mfma16(xf[kk], cf, ar); as = mfma16(xf[kk], sf, as); }
;             const int ka = 16 * i + lr; float tc, ts; sincospif(2.0f * (float)(b * ka) / (float)S, &ts, &tc);
;             const f32x4 re = ar * tc - as * ts, im = -(as * tc) - ar * ts;
;             bf16_t* op = A1 + (sbase + (size_t)ka * 128 + b) * 2048 + cb * 128 + 16 * w + 4 * lq;
;             u32x2 o; o.x = cvt_pk_bf16(re[0], re[1]); o.y = cvt_pk_bf16(re[2], re[3]); *(u32x2*)op = o;
;             o.x = cvt_pk_bf16(im[0], im[1]); o.y = cvt_pk_bf16(im[2], im[3]); *(u32x2*)(op + 1024) = o; }
	v_mfma_f32_16x16x32_bf16 v[38:41], v[30:33], v[46:49], v[38:41]
	v_or_b32_e32 v6, s6, v6
	v_lshlrev_b64 v[44:45], 12, v[6:7]
	v_lshl_add_u64 v[44:45], v[4:5], 0, v[44:45]
	s_waitcnt lgkmcnt(0)
	v_mfma_f32_16x16x32_bf16 v[22:25], v[30:33], v[50:53], v[22:25]
	v_mul_f32_e64 v30, v42, s14
	v_mul_f32_e64 v31, v43, s14
	v_pk_mul_f32 v[32:33], v[30:31], 0.5 op_sel_hi:[1,0]
	s_nop 0
	v_fract_f32_e32 v6, v33
	v_add_f32_e32 v6, v6, v6
	v_cmp_neq_f32_e64 s[0:1], s7, v33
	s_nop 1
	v_cndmask_b32_e64 v6, 0, v6, s[0:1]
	v_cmp_lt_f32_e64 s[0:1], 1.0, v31
	s_nop 1
	v_cndmask_b32_e64 v6, v31, v6, s[0:1]
	v_add_f32_e32 v33, v6, v6
	v_rndne_f32_e32 v33, v33
	v_fmac_f32_e32 v6, -0.5, v33
	v_mul_f32_e32 v42, v6, v6
	v_fmamk_f32 v43, v42, 0x3e75aa41, v58
	v_fmaak_f32 v43, v42, v43, 0x40234736
	v_fmaak_f32 v43, v42, v43, 0xc0a55e0e
	v_mul_f32_e32 v46, v6, v42
	v_mul_f32_e32 v43, v46, v43
	v_cvt_i32_f32_e32 v33, v33
	v_fmac_f32_e32 v43, 0x40490fdb, v6
	v_fmamk_f32 v6, v42, 0x3d4be544, v59
	v_fmaak_f32 v6, v42, v6, 0xbfaad1da
	v_fmaak_f32 v6, v42, v6, 0x4081e0d3
	v_fmaak_f32 v6, v42, v6, 0xc09de9e6
	v_fma_f32 v6, v42, v6, 1.0
	v_lshlrev_b32_e32 v42, 30, v33
	v_and_b32_e32 v33, 1, v33
	v_cmp_eq_u32_e64 s[0:1], 0, v33
	s_nop 1
	v_cndmask_b32_e64 v33, v6, v43, s[0:1]
	v_xor_b32_e32 v43, 0x80000000, v43
	v_bitop3_b32 v33, v33, v42, s10 bitop3:0x78
	v_cndmask_b32_e64 v6, v43, v6, s[0:1]
	v_cmp_lg_f32_e64 s[0:1], s7, v31
	v_bitop3_b32 v6, v6, v42, s10 bitop3:0x78
	s_nop 0
	v_cndmask_b32_e64 v42, v60, v33, s[0:1]
	v_cndmask_b32_e64 v6, v60, v6, s[0:1]
	v_pk_mul_f32 v[46:47], v[42:43], v[34:35] op_sel_hi:[0,1]
	v_pk_mul_f32 v[48:49], v[42:43], v[36:37] op_sel_hi:[0,1]
	v_pk_fma_f32 v[48:49], v[6:7], v[28:29], v[48:49] op_sel_hi:[0,1,1] neg_lo:[0,0,1] neg_hi:[0,0,1]
	v_pk_fma_f32 v[46:47], v[6:7], v[26:27], v[46:47] op_sel_hi:[0,1,1] neg_lo:[0,0,1] neg_hi:[0,0,1]
	v_pk_mul_f32 v[26:27], v[42:43], v[26:27] op_sel_hi:[0,1]
	v_pk_mul_f32 v[28:29], v[42:43], v[28:29] op_sel_hi:[0,1]
	v_pk_fma_f32 v[28:29], v[36:37], v[6:7], v[28:29] op_sel_hi:[1,0,1] neg_lo:[0,1,1] neg_hi:[0,1,1]
	v_pk_fma_f32 v[26:27], v[34:35], v[6:7], v[26:27] op_sel_hi:[1,0,1] neg_lo:[0,1,1] neg_hi:[0,1,1]
	v_fract_f32_e32 v6, v32
	v_add_f32_e32 v6, v6, v6
	v_cmp_neq_f32_e64 s[0:1], s7, v32
	v_cvt_pk_bf16_f32 v26, v26, v27
	v_cvt_pk_bf16_f32 v27, v28, v29
	v_cndmask_b32_e64 v6, 0, v6, s[0:1]
	v_cmp_lt_f32_e64 s[0:1], 1.0, v30
	global_store_dwordx2 v[44:45], v[26:27], off offset:2048
	v_cvt_pk_bf16_f32 v34, v46, v47
	v_cndmask_b32_e64 v6, v30, v6, s[0:1]
	v_add_f32_e32 v26, v6, v6
	v_rndne_f32_e32 v26, v26
	v_fmac_f32_e32 v6, -0.5, v26
	v_mul_f32_e32 v27, v6, v6
	v_fmamk_f32 v28, v27, 0x3e75aa41, v58
	v_fmaak_f32 v28, v27, v28, 0x40234736
	v_fmaak_f32 v28, v27, v28, 0xc0a55e0e
	v_mul_f32_e32 v29, v6, v27
	v_mul_f32_e32 v28, v29, v28
	v_cvt_i32_f32_e32 v26, v26
	v_fmac_f32_e32 v28, 0x40490fdb, v6
	v_fmamk_f32 v6, v27, 0x3d4be544, v59
	v_fmaak_f32 v6, v27, v6, 0xbfaad1da
	v_fmaak_f32 v6, v27, v6, 0x4081e0d3
	v_fmaak_f32 v6, v27, v6, 0xc09de9e6
	v_fma_f32 v6, v27, v6, 1.0
	v_lshlrev_b32_e32 v27, 30, v26
	v_and_b32_e32 v26, 1, v26
	v_cmp_eq_u32_e64 s[0:1], 0, v26
	v_cvt_pk_bf16_f32 v35, v48, v49
	global_store_dwordx2 v[44:45], v[34:35], off
	v_cndmask_b32_e64 v26, v6, v28, s[0:1]
	v_xor_b32_e32 v28, 0x80000000, v28
	v_bitop3_b32 v26, v26, v27, s10 bitop3:0x78
	v_cndmask_b32_e64 v6, v28, v6, s[0:1]
	v_cmp_lg_f32_e64 s[0:1], s7, v30
	v_bitop3_b32 v6, v6, v27, s10 bitop3:0x78
	s_nop 0
	v_cndmask_b32_e64 v26, v60, v26, s[0:1]
	v_cndmask_b32_e64 v6, v60, v6, s[0:1]
	v_pk_mul_f32 v[28:29], v[26:27], v[22:23] op_sel_hi:[0,1]
	v_pk_mul_f32 v[30:31], v[26:27], v[24:25] op_sel_hi:[0,1]
	v_pk_mul_f32 v[32:33], v[26:27], v[38:39] op_sel_hi:[0,1]
	v_pk_mul_f32 v[26:27], v[26:27], v[40:41] op_sel_hi:[0,1]
	v_pk_fma_f32 v[30:31], v[6:7], v[40:41], v[30:31] op_sel_hi:[0,1,1] neg_lo:[0,0,1] neg_hi:[0,0,1]
	v_pk_fma_f32 v[28:29], v[6:7], v[38:39], v[28:29] op_sel_hi:[0,1,1] neg_lo:[0,0,1] neg_hi:[0,0,1]
	v_pk_fma_f32 v[24:25], v[24:25], v[6:7], v[26:27] op_sel_hi:[1,0,1] neg_lo:[0,1,1] neg_hi:[0,1,1]
	v_pk_fma_f32 v[22:23], v[22:23], v[6:7], v[32:33] op_sel_hi:[1,0,1] neg_lo:[0,1,1] neg_hi:[0,1,1]
	v_or_b32_e32 v6, s23, v14
	v_or_b32_e32 v6, s6, v6
	v_lshlrev_b64 v[6:7], 12, v[6:7]
	v_lshl_add_u64 v[4:5], v[4:5], 0, v[6:7]
	v_cvt_pk_bf16_f32 v6, v28, v29
	v_cvt_pk_bf16_f32 v7, v30, v31
	global_store_dwordx2 v[4:5], v[6:7], off
	v_cvt_pk_bf16_f32 v6, v22, v23
	v_cvt_pk_bf16_f32 v7, v24, v25
	global_store_dwordx2 v[4:5], v[6:7], off offset:2048
	s_barrier
	s_cbranch_scc1 .LBB0_333
.LBB0_327:
	s_and_b32 s16, s22, 7
	s_lshl_b32 s36, s16, 7
	s_ashr_i32 s0, s22, 31
	s_lshr_b32 s0, s0, 22
	s_add_i32 s0, s22, s0
	s_ashr_i32 s0, s0, 10
	s_ashr_i32 s1, s0, 31
	s_bfe_u32 s23, s22, 0x70003
	s_lshl_b64 s[6:7], s[0:1], 13
	s_mov_b64 s[10:11], exec
	v_mov_b64_e32 v[4:5], s[36:37]
	s_or_b32 s14, s6, s23
	s_mov_b32 s15, s7
	s_lshl_b32 s0, s16, 8
	s_add_u32 s16, s76, s0
	s_addc_u32 s17, s77, 0
	s_lshl_b64 s[14:15], s[14:15], 11
	s_add_u32 s14, s14, s16
	s_addc_u32 s15, s15, s17
	v_lshl_add_u64 v[204:205], s[14:15], 0, v[200:201]
	s_mov_b64 s[16:17], 0x800000
	global_load_dwordx4 v[206:209], v[204:205], off
	v_lshl_add_u64 v[204:205], v[204:205], 0, s[16:17]
	global_load_dwordx4 v[210:213], v[204:205], off
	s_waitcnt vmcnt(1)
	ds_write_b128 v202, v[206:209]
	s_waitcnt vmcnt(0)
	ds_write_b128 v202, v[210:213] offset:8192
	s_branch .LBB0_326
